# GQA/MLA tile loops: MFMA C-init registers kept valid across the 4-tile iteration (8 v_mov_b64 per iteration removed; temporaries moved to spare registers)
# baseline (speedup 1.0000x reference)
; __device__ __forceinline__ unsigned cvtpk(float lo, float hi) { typedef __bf16 bf2 __attribute__((ext_vector_type(2))); f32x2 v = {lo, hi}; bf2 b = __builtin_convertvector(v, bf2); return __builtin_bit_cast(unsigned, b); }
; template <int DQK, int DV, bool BIAS> ...
;     ...
;     bf16x8 qf[NKS];
; #pragma unroll
;     for (int ks = 0; ks < NKS; ++ks) qf[ks] = ks < 4 ? *(const bf16x8*)(Qw + (size_t)r32 * ldq + ks * 16 + hi * 8) : *(const bf16x8*)(Q2w + (size_t)r32 * ldq2 + (ks - 4) * 16 + hi * 8);
; #pragma unroll
;     for (int ks = 0; ks < 4; ++ks) qf[ks] = scale_frag(qf[ks], cs);
;     if constexpr (DQK == 96) {
;         const float* rp = ropetab + ((size_t)(qpos0 + r32) * 16) * 2;
; #pragma unroll
;         for (int ks = 4; ks < 6; ++ks) {
;             const f32x4 c0 = *(const f32x4*)(rp + ((ks - 4) * 8 + hi * 4) * 2), c1 = *(const f32x4*)(rp + ((ks - 4) * 8 + hi * 4 + 2) * 2);
;             const u32x4 w = __builtin_bit_cast(u32x4, qf[ks]); u32x4 ow;
;             { const float a = bflo(w.x) * cs, b = bfhi(w.x) * cs; ow.x = cvtpk(a * c0[0] - b * c0[1], a * c0[1] + b * c0[0]); }
;             { const float a = bflo(w.y) * cs, b = bfhi(w.y) * cs; ow.y = cvtpk(a * c0[2] - b * c0[3], a * c0[3] + b * c0[2]); }
;             { const float a = bflo(w.z) * cs, b = bfhi(w.z) * cs; ow.z = cvtpk(a * c1[0] - b * c1[1], a * c1[1] + b * c1[0]); }
;             { const float a = bflo(w.w) * cs, b = bfhi(w.w) * cs; ow.w = cvtpk(a * c1[2] - b * c1[3], a * c1[3] + b * c1[2]); }
;             qf[ks] = __builtin_bit_cast(bf16x8, ow);
;         }
;     }
; #pragma unroll
;     for (int d = 0; d < NDT; ++d)
; #pragma unroll
;         for (int r = 0; r < 16; ++r) o[d][r] = 0.f;
; #pragma unroll
;     for (int ks = 0; ks < NKS; ++ks) asm volatile("" : "+v"(qf[ks]));
;     float mhat = 0.f, l = 0.f; f32x16 negm;
; #pragma unroll
;     for (int r = 0; r < 16; ++r) negm[r] = 0.f;
;     constexpr int TPB = (DV == 64) ? 2 : 1, NG = SEQL / 64 / TPB;
;     u32x4 kreg[TPB], k2reg[TPB], vreg[TPB][NVL];
;     const bf16_t* kptr = Kg + (size_t)(tid >> 3) * ldk + (tid & 7) * 8;
;     const bf16_t* k2ptr = (DQK == 96) ? K2g + (size_t)(tid >> 2) * ldk2 + (tid & 3) * 8 : nullptr;
;     ...
;     u32x4 pw[4];
; #pragma unroll
;     for (int j = 0; j < TPB; ++j) { ATT_LOAD(j, j); ATT_STORE(j, j); }
; #pragma unroll
;     for (int j = 0; j < TPB; ++j) ATT_LOAD(TPB + j, j);
.LBB0_600:
	s_xor_b64 s[8:9], s[10:11], -1
	s_add_i32 s10, s20, s33
	s_ashr_i32 s18, s10, 7
	s_ashr_i32 s19, s18, 31
	s_lshl_b64 s[10:11], s[18:19], 12
	s_add_u32 s10, s10, s27
	s_addc_u32 s11, s11, s48
	s_mulk_i32 s11, 0x1940
	s_mul_hi_u32 s19, s10, 0x1940
	v_mov_b32_e32 v34, v1
	s_add_i32 s19, s19, s11
	s_mulk_i32 s10, 0x1940
	s_add_u32 s10, s35, s10
	v_and_b32_e32 v35, 31, v34
	v_mul_u32_u24_e32 v2, 0xca0, v35
	s_addc_u32 s11, s36, s19
	v_bfe_u32 v36, v34, 5, 1
	v_lshlrev_b32_e32 v130, 1, v2
	v_lshl_add_u64 v[2:3], s[10:11], 0, v[130:131]
	v_lshlrev_b32_e32 v130, 4, v36
	v_lshl_add_u64 v[18:19], v[2:3], 0, v[130:131]
	global_load_dwordx4 v[2:5], v[18:19], off offset:3072
	global_load_dwordx4 v[6:9], v[18:19], off offset:3104
	global_load_dwordx4 v[10:13], v[18:19], off offset:3136
	global_load_dwordx4 v[14:17], v[18:19], off offset:3168
	s_mul_i32 s20, s18, 0x1940000
	s_mul_hi_i32 s19, s18, 0x1940000
	s_add_u32 s20, s16, s20
	s_addc_u32 s19, s17, s19
	s_add_u32 s20, s20, s38
	s_addc_u32 s21, s19, 0
	s_add_u32 s22, s20, 0x1000
	s_addc_u32 s23, s21, 0
	v_lshlrev_b32_e32 v36, 8, v36
	v_mad_u32_u24 v35, v35, s39, 0
	v_add_u32_e32 v130, v35, v130
	v_mov_b32_e32 v144, 0
	v_mov_b32_e32 v143, 0
	v_mov_b32_e32 v50, 0
	v_mov_b32_e32 v51, v131
	v_mov_b32_e32 v52, v131
	v_mov_b32_e32 v53, v131
	v_mov_b32_e32 v54, v131
	v_mov_b32_e32 v55, v131
	v_mov_b32_e32 v56, v131
	v_mov_b32_e32 v57, v131
	v_mov_b32_e32 v58, v131
	v_mov_b32_e32 v59, v131
	v_mov_b32_e32 v60, v131
	v_mov_b32_e32 v61, v131
	v_mov_b32_e32 v62, v131
	v_mov_b32_e32 v63, v131
	v_mov_b32_e32 v64, v131
	v_mov_b32_e32 v65, v131
	s_waitcnt vmcnt(3)
	v_lshlrev_b32_e32 v18, 16, v2
	v_and_b32_e32 v19, 0xffff0000, v2
	v_lshlrev_b32_e32 v2, 16, v3
	v_and_b32_e32 v3, 0xffff0000, v3
	s_waitcnt vmcnt(0)
	v_lshlrev_b32_e32 v30, 16, v14
	v_and_b32_e32 v31, 0xffff0000, v14
	v_lshlrev_b32_e32 v32, 16, v16
	v_and_b32_e32 v33, 0xffff0000, v16
	v_lshlrev_b32_e32 v16, 16, v17
	v_pk_mul_f32 v[2:3], v[2:3], s[6:7] op_sel_hi:[1,0]
	v_and_b32_e32 v17, 0xffff0000, v17
	v_pk_mul_f32 v[30:31], v[30:31], s[6:7] op_sel_hi:[1,0]
	v_pk_mul_f32 v[32:33], v[32:33], s[6:7] op_sel_hi:[1,0]
	v_cvt_pk_bf16_f32 v99, v2, v3
	v_pk_mul_f32 v[2:3], v[16:17], s[6:7] op_sel_hi:[1,0]
	v_lshlrev_b32_e32 v20, 16, v4
	v_and_b32_e32 v21, 0xffff0000, v4
	v_pk_mul_f32 v[18:19], v[18:19], s[6:7] op_sel_hi:[1,0]
	v_cvt_pk_bf16_f32 v110, v30, v31
	v_cvt_pk_bf16_f32 v112, v32, v33
	v_cvt_pk_bf16_f32 v113, v2, v3
	v_ashrrev_i32_e32 v30, 3, v34
	v_mov_b64_e32 v[2:3], s[22:23]
	v_lshlrev_b32_e32 v32, 4, v34
	v_lshlrev_b32_e32 v4, 16, v5
	v_and_b32_e32 v5, 0xffff0000, v5
	v_pk_mul_f32 v[20:21], v[20:21], s[6:7] op_sel_hi:[1,0]
	v_cvt_pk_bf16_f32 v98, v18, v19
	v_mad_i64_i32 v[2:3], s[22:23], v30, s37, v[2:3]
	v_and_b32_e32 v18, 0x70, v32
	v_mov_b32_e32 v19, v131
	v_lshlrev_b32_e32 v22, 16, v6
	v_and_b32_e32 v23, 0xffff0000, v6
	v_pk_mul_f32 v[4:5], v[4:5], s[6:7] op_sel_hi:[1,0]
	v_cvt_pk_bf16_f32 v100, v20, v21
	v_lshl_add_u64 v[20:21], v[2:3], 0, v[18:19]
	v_and_b32_e32 v2, 0xffffffe0, v30
	v_pk_mul_f32 v[22:23], v[22:23], s[6:7] op_sel_hi:[1,0]
	v_cvt_pk_bf16_f32 v101, v4, v5
	v_ashrrev_i32_e32 v3, 31, v2
	v_lshlrev_b32_e32 v4, 3, v34
	v_cvt_pk_bf16_f32 v102, v22, v23
	v_lshlrev_b64 v[22:23], 1, v[2:3]
	v_and_b32_e32 v37, 24, v4
	v_bfe_u32 v33, v34, 2, 6
	v_lshl_add_u64 v[2:3], s[20:21], 0, v[22:23]
	v_lshlrev_b32_e32 v4, 1, v37
	v_mov_b32_e32 v5, v131
	v_lshlrev_b32_e32 v24, 16, v8
	v_and_b32_e32 v25, 0xffff0000, v8
	v_lshl_add_u64 v[2:3], v[2:3], 0, v[4:5]
	v_mul_u32_u24_e32 v4, 0xca0, v33
	v_lshlrev_b32_e32 v26, 16, v10
	v_and_b32_e32 v27, 0xffff0000, v10
	v_lshlrev_b32_e32 v10, 16, v11
	v_and_b32_e32 v11, 0xffff0000, v11
	v_pk_mul_f32 v[24:25], v[24:25], s[6:7] op_sel_hi:[1,0]
	v_lshlrev_b32_e32 v4, 1, v4
	v_pk_mul_f32 v[10:11], v[10:11], s[6:7] op_sel_hi:[1,0]
	v_cvt_pk_bf16_f32 v104, v24, v25
	v_lshl_add_u64 v[24:25], v[2:3], 0, v[4:5]
	v_cvt_pk_bf16_f32 v107, v10, v11
	v_add_co_u32_e32 v10, vcc, s40, v24
	v_pk_mul_f32 v[26:27], v[26:27], s[6:7] op_sel_hi:[1,0]
	s_nop 0
	v_addc_co_u32_e32 v11, vcc, 0, v25, vcc
	v_lshlrev_b32_e32 v28, 16, v12
	v_and_b32_e32 v29, 0xffff0000, v12
	v_cvt_pk_bf16_f32 v106, v26, v27
	v_add_co_u32_e32 v26, vcc, s41, v20
	v_lshlrev_b32_e32 v6, 16, v7
	v_and_b32_e32 v7, 0xffff0000, v7
	v_lshlrev_b32_e32 v8, 16, v9
	v_and_b32_e32 v9, 0xffff0000, v9
	v_lshlrev_b32_e32 v12, 16, v13
	v_and_b32_e32 v13, 0xffff0000, v13
	v_lshlrev_b32_e32 v14, 16, v15
	v_and_b32_e32 v15, 0xffff0000, v15
	v_pk_mul_f32 v[28:29], v[28:29], s[6:7] op_sel_hi:[1,0]
	v_addc_co_u32_e32 v27, vcc, 0, v21, vcc
	v_pk_mul_f32 v[6:7], v[6:7], s[6:7] op_sel_hi:[1,0]
	v_pk_mul_f32 v[8:9], v[8:9], s[6:7] op_sel_hi:[1,0]
	v_pk_mul_f32 v[12:13], v[12:13], s[6:7] op_sel_hi:[1,0]
	v_pk_mul_f32 v[14:15], v[14:15], s[6:7] op_sel_hi:[1,0]
	v_cvt_pk_bf16_f32 v108, v28, v29
	v_add_co_u32_e32 v28, vcc, s42, v24
	v_cvt_pk_bf16_f32 v103, v6, v7
	v_cvt_pk_bf16_f32 v105, v8, v9
	v_cvt_pk_bf16_f32 v109, v12, v13
	v_cvt_pk_bf16_f32 v111, v14, v15
	v_addc_co_u32_e32 v29, vcc, 0, v25, vcc
	global_load_dwordx4 v[2:5], v[20:21], off
	global_load_dwordx4 v[6:9], v[10:11], off offset:256
	s_nop 0
	global_load_dwordx4 v[10:13], v[26:27], off
	global_load_dwordx4 v[14:17], v[28:29], off offset:256
	v_add_co_u32_e32 v28, vcc, s44, v24
	v_mad_i64_i32 v[26:27], s[20:21], v30, s37, 0
	s_nop 0
	v_addc_co_u32_e32 v29, vcc, 0, v25, vcc
	v_add_co_u32_e32 v24, vcc, s46, v24
	v_mul_lo_u32 v38, v30, s39
	s_nop 0
	v_addc_co_u32_e32 v25, vcc, 0, v25, vcc
	v_add_co_u32_e32 v30, vcc, s43, v20
	v_and_b32_e32 v39, 0xfffff000, v32
	s_nop 0
	v_addc_co_u32_e32 v31, vcc, 0, v21, vcc
	v_add_co_u32_e32 v20, vcc, s45, v20
	v_and_b32_e32 v40, 0xfc0, v32
	s_nop 0
	v_addc_co_u32_e32 v21, vcc, 0, v21, vcc
	global_load_dwordx4 v[114:117], v[30:31], off
	global_load_dwordx4 v[118:121], v[28:29], off offset:256
	global_load_dwordx4 v[122:125], v[20:21], off
	global_load_dwordx4 v[126:129], v[24:25], off offset:256
	v_add_u32_e32 v20, 0, v38
	v_and_b32_e32 v41, 48, v32
	v_add3_u32 v21, 0, v39, v40
	v_add_u32_e32 v133, v20, v18
	v_add_u32_e32 v140, v21, v41
	s_waitcnt vmcnt(7)
; #define LAS __attribute__((address_space(3)))
; __device__ __forceinline__ unsigned cvtpk(float lo, float hi) { typedef __bf16 bf2 __attribute__((ext_vector_type(2))); f32x2 v = {lo, hi}; bf2 b = __builtin_convertvector(v, bf2); return __builtin_bit_cast(unsigned, b); }
; template <int DQK, int DV, bool BIAS> ...
;     ...
;     u32x4 pw[4];
; #pragma unroll
;     for (int j = 0; j < TPB; ++j) { ATT_LOAD(j, j); ATT_STORE(j, j); }
; #pragma unroll
;     for (int j = 0; j < TPB; ++j) ATT_LOAD(TPB + j, j);
;     const float qp = (float)(qpos0 + r32);
; #pragma unroll 2
;     for (int g = 0; g < NG; ++g) {
;         const int pair = g & 1;
;         __syncthreads();
;         if (g + 1 < NG) {
; #pragma unroll
;             for (int j = 0; j < TPB; ++j) ATT_STORE((pair ^ 1) * TPB + j, j);
;     ...
;         if (!isY) {
;             const LAS unsigned char* vbase = lds + VOFF + vcur * VBUF + (4 * hi + ((lane & 15) >> 2)) * 64 + ((lane >> 4) & 1) * 32 + (lane & 3) * 8;
;             float ls = 0.f;
; #pragma unroll
;             for (int hs = 0; hs < 4; ++hs) {
;                 float e[8];
; #pragma unroll
;                 for (int j = 0; j < 8; ++j) { e[j] = __builtin_amdgcn_exp2f(hs < 2 ? p0[8 * (hs & 1) + j] : p1[8 * (hs & 1) + j]); ls += e[j]; }
;                 pw[hs].x = cvtpk(e[0], e[1]); pw[hs].y = cvtpk(e[2], e[3]); pw[hs].z = cvtpk(e[4], e[5]); pw[hs].w = cvtpk(e[6], e[7]);
;                 const bf16x8 pbv = __builtin_bit_cast(bf16x8, pw[hs]);
; #pragma unroll
;                 for (int d = 0; d < NDT; ++d) { const LAS unsigned char* vp = vbase + d * 4096 + hs * 1024;
;                     const v4i16_t a0 = __builtin_amdgcn_ds_read_tr16_b64_v4i16((LAS v4i16_t*)vp), a1 = __builtin_amdgcn_ds_read_tr16_b64_v4i16((LAS v4i16_t*)(vp + 512));
;                     const bf16x8 av = {a0[0], a0[1], a0[2], a0[3], a1[0], a1[1], a1[2], a1[3]};
;                     o[d] = __builtin_amdgcn_mfma_f32_32x32x16_bf16(av, pbv, o[d], 0, 0, 0); }
;                 __builtin_amdgcn_sched_barrier(0);
;             }
;             l += ls;
	ds_write_b128 v133, v[2:5]
	s_waitcnt vmcnt(6)
	ds_write_b128 v140, v[6:9] offset:36864
	s_waitcnt vmcnt(5)
	ds_write_b128 v133, v[10:13] offset:9216
	s_waitcnt vmcnt(4)
	ds_write_b128 v140, v[14:17] offset:45056
	v_and_b32_e32 v2, 0xc0, v32
	v_lshlrev_b32_e32 v3, 1, v34
	v_add3_u32 v2, 0, v36, v2
	v_and_b32_e32 v3, 32, v3
	v_add3_u32 v141, v2, v3, v37
	v_mul_hi_u32_u24_e32 v3, 0x1940, v33
	v_mul_u32_u24_e32 v2, 0x1940, v33
	v_mad_i64_i32 v[2:3], s[20:21], s18, v139, v[2:3]
	v_and_b32_e32 v4, 3, v34
	v_lshl_or_b32 v2, v4, 4, v2
	v_lshl_add_u64 v[2:3], v[2:3], 0, v[22:23]
	v_mov_b32_e32 v224, v2
	v_lshl_add_u64 v[134:135], s[4:5], 0, v[2:3]
	v_mad_i64_i32 v[2:3], s[18:19], s18, v139, v[26:27]
	v_lshl_add_u64 v[2:3], v[2:3], 0, v[18:19]
	v_add_u32_e32 v142, 0x9000, v141
	v_mov_b32_e32 v225, v2
	v_lshl_add_u64 v[136:137], s[4:5], 0, v[2:3]
	v_mov_b32_e32 v18, v131
	v_mov_b32_e32 v20, v131
	v_mov_b32_e32 v21, v131
	v_mov_b32_e32 v22, v131
	v_mov_b32_e32 v23, v131
	v_mov_b32_e32 v24, v131
	v_mov_b32_e32 v25, v131
	v_mov_b32_e32 v26, v131
	v_mov_b32_e32 v27, v131
	v_mov_b32_e32 v28, v131
	v_mov_b32_e32 v29, v131
	v_mov_b32_e32 v30, v131
	v_mov_b32_e32 v31, v131
	v_mov_b32_e32 v32, v131
	v_mov_b32_e32 v33, v131
	v_mov_b32_e32 v2, v131
	v_mov_b32_e32 v3, v131
	v_mov_b32_e32 v4, v131
	v_mov_b32_e32 v5, v131
	v_mov_b32_e32 v6, v131
	v_mov_b32_e32 v7, v131
	v_mov_b32_e32 v8, v131
	v_mov_b32_e32 v9, v131
	v_mov_b32_e32 v10, v131
	v_mov_b32_e32 v11, v131
	v_mov_b32_e32 v12, v131
	v_mov_b32_e32 v13, v131
	v_mov_b32_e32 v14, v131
	v_mov_b32_e32 v15, v131
	v_mov_b32_e32 v16, v131
	v_mov_b32_e32 v17, v131
	s_mov_b64 s[18:19], 0
	s_mov_b32 s22, 0
	v_mov_b32_e32 v34, 0
	v_mov_b32_e32 v35, 0
	v_mov_b32_e32 v36, 0
	v_mov_b32_e32 v37, 0
	v_mov_b32_e32 v38, 0
	v_mov_b32_e32 v39, 0
	v_mov_b32_e32 v40, 0
	v_mov_b32_e32 v41, 0
	v_mov_b32_e32 v42, 0
	v_mov_b32_e32 v43, 0
	v_mov_b32_e32 v44, 0
	v_mov_b32_e32 v45, 0
	v_mov_b32_e32 v46, 0
	v_mov_b32_e32 v47, 0
	v_mov_b32_e32 v48, 0
	v_mov_b32_e32 v49, 0
	s_branch .LBB0_602
.LBB0_601:
	s_nop 4
	v_exp_f32_e32 v83, v66
	v_exp_f32_e32 v88, v67
	v_exp_f32_e32 v89, v68
	v_exp_f32_e32 v90, v69
	v_exp_f32_e32 v91, v70
	v_exp_f32_e32 v92, v71
	ds_read_b64_tr_b16 v[66:67], v141 offset:61440
	ds_read_b64_tr_b16 v[68:69], v141 offset:61952
	v_exp_f32_e32 v93, v72
	v_exp_f32_e32 v94, v73
	ds_read_b64_tr_b16 v[84:85], v142 offset:28672
	ds_read_b64_tr_b16 v[86:87], v142 offset:29184
	v_cvt_pk_bf16_f32 v70, v83, v88
	v_cvt_pk_bf16_f32 v71, v89, v90
	v_cvt_pk_bf16_f32 v72, v91, v92
	v_cvt_pk_bf16_f32 v73, v93, v94
	s_waitcnt lgkmcnt(2)
	s_nop 0
	v_mfma_f32_32x32x16_bf16 v[18:33], v[66:69], v[70:73], v[18:33]
	v_add_f32_e32 v66, v88, v83
	v_add_f32_e32 v66, v89, v66
	v_add_f32_e32 v66, v90, v66
	v_add_f32_e32 v66, v91, v66
	v_add_f32_e32 v66, v92, v66
	v_add_f32_e32 v66, v93, v66
	s_waitcnt lgkmcnt(0)
	v_mfma_f32_32x32x16_bf16 v[2:17], v[84:87], v[70:73], v[2:17]
	v_add_f32_e32 v83, v94, v66
	v_exp_f32_e32 v84, v74
	v_exp_f32_e32 v85, v75
	v_exp_f32_e32 v86, v76
	v_exp_f32_e32 v87, v77
	v_exp_f32_e32 v78, v78
	v_exp_f32_e32 v79, v79
	ds_read_b64_tr_b16 v[66:67], v141 offset:62464
	ds_read_b64_tr_b16 v[68:69], v141 offset:62976
	v_exp_f32_e32 v80, v80
	v_exp_f32_e32 v81, v81
	ds_read_b64_tr_b16 v[74:75], v142 offset:29696
	ds_read_b64_tr_b16 v[76:77], v142 offset:30208
	v_cvt_pk_bf16_f32 v70, v84, v85
	v_cvt_pk_bf16_f32 v71, v86, v87
	v_cvt_pk_bf16_f32 v72, v78, v79
	v_cvt_pk_bf16_f32 v73, v80, v81
	s_waitcnt lgkmcnt(2)
	s_nop 0
	v_mfma_f32_32x32x16_bf16 v[18:33], v[66:69], v[70:73], v[18:33]
	v_add_f32_e32 v66, v84, v83
	v_add_f32_e32 v66, v85, v66
	v_add_f32_e32 v66, v86, v66
	v_add_f32_e32 v66, v87, v66
	v_add_f32_e32 v66, v78, v66
	v_add_f32_e32 v66, v79, v66
	v_add_f32_e32 v66, v80, v66
	s_waitcnt lgkmcnt(0)
	v_mfma_f32_32x32x16_bf16 v[2:17], v[74:77], v[70:73], v[2:17]
	v_add_f32_e32 v70, v81, v66
	v_exp_f32_e32 v71, v208
	v_exp_f32_e32 v72, v209
	v_exp_f32_e32 v73, v210
	v_exp_f32_e32 v74, v211
	v_exp_f32_e32 v75, v212
	v_exp_f32_e32 v76, v213
	ds_read_b64_tr_b16 v[208:209], v141 offset:63488
	ds_read_b64_tr_b16 v[210:211], v141 offset:64000
	v_exp_f32_e32 v77, v214
	v_exp_f32_e32 v78, v215
	ds_read_b64_tr_b16 v[66:67], v142 offset:30720
	ds_read_b64_tr_b16 v[68:69], v142 offset:31232
	v_cvt_pk_bf16_f32 v212, v71, v72
	v_cvt_pk_bf16_f32 v213, v73, v74
	v_cvt_pk_bf16_f32 v214, v75, v76
	v_cvt_pk_bf16_f32 v215, v77, v78
	s_waitcnt lgkmcnt(2)
	s_nop 0
	v_mfma_f32_32x32x16_bf16 v[18:33], v[208:211], v[212:215], v[18:33]
	v_add_f32_e32 v208, v71, v70
	v_add_f32_e32 v208, v72, v208
	v_add_f32_e32 v208, v73, v208
	v_add_f32_e32 v208, v74, v208
	v_add_f32_e32 v208, v75, v208
	v_add_f32_e32 v208, v76, v208
	v_add_f32_e32 v208, v77, v208
	s_waitcnt lgkmcnt(0)
	v_mfma_f32_32x32x16_bf16 v[2:17], v[66:69], v[212:215], v[2:17]
	v_add_f32_e32 v66, v78, v208
	v_exp_f32_e32 v67, v216
	v_exp_f32_e32 v68, v217
	v_exp_f32_e32 v69, v218
	v_exp_f32_e32 v70, v219
	v_exp_f32_e32 v220, v220
	v_exp_f32_e32 v221, v221
	ds_read_b64_tr_b16 v[208:209], v141 offset:64512
	ds_read_b64_tr_b16 v[210:211], v141 offset:65024
	v_exp_f32_e32 v222, v222
	v_exp_f32_e32 v223, v223
	ds_read_b64_tr_b16 v[216:217], v142 offset:31744
	ds_read_b64_tr_b16 v[218:219], v142 offset:32256
	v_cvt_pk_bf16_f32 v212, v67, v68
	v_cvt_pk_bf16_f32 v213, v69, v70
	v_cvt_pk_bf16_f32 v214, v220, v221
	v_cvt_pk_bf16_f32 v215, v222, v223
	s_waitcnt lgkmcnt(2)
	s_nop 0
	v_mfma_f32_32x32x16_bf16 v[18:33], v[208:211], v[212:215], v[18:33]
	v_add_f32_e32 v208, v67, v66
	v_add_f32_e32 v208, v68, v208
	v_add_f32_e32 v208, v69, v208
	v_add_f32_e32 v208, v70, v208
	v_add_f32_e32 v208, v220, v208
	v_add_f32_e32 v208, v221, v208
	v_add_f32_e32 v208, v222, v208
	s_waitcnt lgkmcnt(0)
	v_mfma_f32_32x32x16_bf16 v[2:17], v[216:219], v[212:215], v[2:17]
	v_add_f32_e32 v208, v223, v208
	s_add_u32 s18, s18, 0x194000
	s_addc_u32 s19, s19, 0
	s_add_i32 s22, s22, 2
	s_cmp_lg_u32 s18, 0x1940000
	v_add_f32_e32 v144, v82, v208
	s_cbranch_scc0 .LBB0_599

; #define LAS __attribute__((address_space(3)))
; __device__ __forceinline__ float max3f(float a, float b, float c) { float r; asm("v_max3_f32 %0, %1, %2, %3" : "=v"(r) : "v"(a), "v"(b), "v"(c)); return r; }
; template <int DQK, int DV, bool BIAS> ...
;     ...
; #pragma unroll
;       for (int sub = 0; sub < TPB; ++sub) {
;         const int t = g * TPB + sub, buf = pair * TPB + sub, vcur = buf;
;         f32x16 p0, p1;
;         const LAS unsigned char* kb = lds + buf * KBUF + r32 * KP + hi * 16;
; #pragma unroll
;         for (int ks = 0; ks < NKS; ++ks) {
;             const bf16x8 k0 = *(const LAS bf16x8*)(kb + ks * 32), k1 = *(const LAS bf16x8*)(kb + 32 * KP + ks * 32);
;             if (ks == 0) { p0 = __builtin_amdgcn_mfma_f32_32x32x16_bf16(k0, qf[0], negm, 0, 0, 0); p1 = __builtin_amdgcn_mfma_f32_32x32x16_bf16(k1, qf[0], negm, 0, 0, 0); }
;             else { p0 = __builtin_amdgcn_mfma_f32_32x32x16_bf16(k0, qf[ks], p0, 0, 0, 0); p1 = __builtin_amdgcn_mfma_f32_32x32x16_bf16(k1, qf[ks], p1, 0, 0, 0); }
;         }
;         if (BIAS) {
;             asm volatile("s_nop 15\n\ts_nop 7" : "+v"(p0), "+v"(p1));
;             const float d0 = qp - (float)(t * 64 + 4 * hi);
; #pragma unroll
;             for (int r = 0; r < 16; ++r) { const float dk = d0 - (float)((r & 3) + 8 * (r >> 2)); p0[r] = p0[r] - sl2 * fabsf(dk); p1[r] = p1[r] - sl2 * fabsf(dk - 32.f); }
;         } else {
;             asm volatile("s_nop 15\n\ts_nop 7" : "+v"(p0), "+v"(p1));
;         }
;         float mxa = max3f(p0[0], p0[1], p1[0]), mxb = max3f(p0[2], p0[3], p1[1]); mxa = max3f(mxa, p1[2], p1[3]);
; #pragma unroll
;         for (int r = 4; r < 16; r += 4) { mxa = max3f(mxa, p0[r], p0[r + 1]); mxb = max3f(mxb, p0[r + 2], p0[r + 3]); mxa = max3f(mxa, p1[r], p1[r + 1]); mxb = max3f(mxb, p1[r + 2], p1[r + 3]); }
;         float mx = fmaxf(mxa, mxb);
;         if (__any(mx > 8.f)) {
;             mx = fmaxf(mx, __shfl_xor(mx, 32));
;             const float dl = fmaxf(mx, 0.f); mhat += dl;
;             const float f = __builtin_amdgcn_exp2f(-dl);
; #pragma unroll
;             for (int r = 0; r < 16; ++r) { p0[r] -= dl; p1[r] -= dl; negm[r] = -mhat; }
;             l *= f;
; #pragma unroll
;             for (int d = 0; d < NDT; ++d)
; #pragma unroll
;                 for (int r = 0; r < 16; ++r) o[d][r] *= f;
;         }
.LBB0_604:
	ds_read_b128 v[208:211], v130
	ds_read_b128 v[212:215], v130 offset:32
	s_waitcnt lgkmcnt(1)
	v_mfma_f32_32x32x16_bf16 v[82:97], v[208:211], v[98:101], v[50:65]
	ds_read_b128 v[208:211], v130 offset:4608
	ds_read_b128 v[216:219], v130 offset:4640
	s_waitcnt lgkmcnt(1)
	v_mfma_f32_32x32x16_bf16 v[66:81], v[208:211], v[98:101], v[50:65]
	v_mfma_f32_32x32x16_bf16 v[82:97], v[212:215], v[102:105], v[82:97]
	ds_read_b128 v[208:211], v130 offset:64
	ds_read_b128 v[212:215], v130 offset:96
	s_waitcnt lgkmcnt(2)
	v_mfma_f32_32x32x16_bf16 v[66:81], v[216:219], v[102:105], v[66:81]
	s_waitcnt lgkmcnt(1)
	v_mfma_f32_32x32x16_bf16 v[82:97], v[208:211], v[106:109], v[82:97]
	ds_read_b128 v[208:211], v130 offset:4672
	ds_read_b128 v[216:219], v130 offset:4704
	s_waitcnt lgkmcnt(1)
	v_mfma_f32_32x32x16_bf16 v[66:81], v[208:211], v[106:109], v[66:81]
	v_mfma_f32_32x32x16_bf16 v[82:97], v[212:215], v[110:113], v[82:97]
	s_waitcnt lgkmcnt(0)
	v_mfma_f32_32x32x16_bf16 v[66:81], v[216:219], v[110:113], v[66:81]
	s_nop 15
	s_nop 7
	s_nop 0
	v_max3_f32 v226, v82, v83, v66
	v_max3_f32 v227, v84, v85, v67
	v_max3_f32 v226, v226, v68, v69
	v_max3_f32 v227, v227, v88, v89
	v_max3_f32 v226, v226, v86, v87
	v_max3_f32 v227, v227, v72, v73
	v_max3_f32 v226, v226, v70, v71
	v_max3_f32 v227, v227, v92, v93
	v_max3_f32 v226, v226, v90, v91
	v_max3_f32 v227, v227, v76, v77
	v_max3_f32 v226, v226, v74, v75
	v_max3_f32 v227, v227, v96, v97
	v_max3_f32 v226, v226, v94, v95
	v_max3_f32 v227, v227, v80, v81
	v_max3_f32 v226, v226, v78, v79
	v_max_f32_e32 v226, v226, v227
	v_cmp_lt_f32_e32 vcc, s47, v226
	s_cbranch_vccz .LBB0_606
	ds_bpermute_b32 v227, v168, v226
	s_waitcnt lgkmcnt(0)
	v_max3_f32 v36, v226, v227, 0
	v_exp_f32_e64 v38, -v36
	v_add_f32_e32 v143, v143, v36
	v_xor_b32_e32 v34, 0x80000000, v143
	v_pk_add_f32 v[82:83], v[82:83], v[36:37] op_sel_hi:[1,0] neg_lo:[0,1] neg_hi:[0,1]
	v_pk_add_f32 v[66:67], v[66:67], v[36:37] op_sel_hi:[1,0] neg_lo:[0,1] neg_hi:[0,1]
	v_pk_add_f32 v[84:85], v[84:85], v[36:37] op_sel_hi:[1,0] neg_lo:[0,1] neg_hi:[0,1]
	v_pk_add_f32 v[68:69], v[68:69], v[36:37] op_sel_hi:[1,0] neg_lo:[0,1] neg_hi:[0,1]
	v_pk_add_f32 v[86:87], v[86:87], v[36:37] op_sel_hi:[1,0] neg_lo:[0,1] neg_hi:[0,1]
	v_pk_add_f32 v[70:71], v[70:71], v[36:37] op_sel_hi:[1,0] neg_lo:[0,1] neg_hi:[0,1]
	v_pk_add_f32 v[88:89], v[88:89], v[36:37] op_sel_hi:[1,0] neg_lo:[0,1] neg_hi:[0,1]
	v_pk_add_f32 v[72:73], v[72:73], v[36:37] op_sel_hi:[1,0] neg_lo:[0,1] neg_hi:[0,1]
	v_pk_add_f32 v[90:91], v[90:91], v[36:37] op_sel_hi:[1,0] neg_lo:[0,1] neg_hi:[0,1]
	v_pk_add_f32 v[74:75], v[74:75], v[36:37] op_sel_hi:[1,0] neg_lo:[0,1] neg_hi:[0,1]
	v_pk_add_f32 v[92:93], v[92:93], v[36:37] op_sel_hi:[1,0] neg_lo:[0,1] neg_hi:[0,1]
	v_pk_add_f32 v[76:77], v[76:77], v[36:37] op_sel_hi:[1,0] neg_lo:[0,1] neg_hi:[0,1]
	v_pk_add_f32 v[94:95], v[94:95], v[36:37] op_sel_hi:[1,0] neg_lo:[0,1] neg_hi:[0,1]
	v_pk_add_f32 v[78:79], v[78:79], v[36:37] op_sel_hi:[1,0] neg_lo:[0,1] neg_hi:[0,1]
	v_pk_add_f32 v[96:97], v[96:97], v[36:37] op_sel_hi:[1,0] neg_lo:[0,1] neg_hi:[0,1]
	v_pk_add_f32 v[80:81], v[80:81], v[36:37] op_sel_hi:[1,0] neg_lo:[0,1] neg_hi:[0,1]
	v_pk_mul_f32 v[16:17], v[16:17], v[38:39] op_sel_hi:[1,0]
	v_pk_mul_f32 v[14:15], v[14:15], v[38:39] op_sel_hi:[1,0]
	v_pk_mul_f32 v[12:13], v[12:13], v[38:39] op_sel_hi:[1,0]
	v_pk_mul_f32 v[10:11], v[10:11], v[38:39] op_sel_hi:[1,0]
	v_pk_mul_f32 v[8:9], v[8:9], v[38:39] op_sel_hi:[1,0]
	v_pk_mul_f32 v[6:7], v[6:7], v[38:39] op_sel_hi:[1,0]
	v_pk_mul_f32 v[4:5], v[4:5], v[38:39] op_sel_hi:[1,0]
	v_pk_mul_f32 v[2:3], v[2:3], v[38:39] op_sel_hi:[1,0]
	v_pk_mul_f32 v[32:33], v[32:33], v[38:39] op_sel_hi:[1,0]
	v_pk_mul_f32 v[30:31], v[30:31], v[38:39] op_sel_hi:[1,0]
	v_pk_mul_f32 v[28:29], v[28:29], v[38:39] op_sel_hi:[1,0]
	v_pk_mul_f32 v[26:27], v[26:27], v[38:39] op_sel_hi:[1,0]
	v_pk_mul_f32 v[24:25], v[24:25], v[38:39] op_sel_hi:[1,0]
	v_pk_mul_f32 v[22:23], v[22:23], v[38:39] op_sel_hi:[1,0]
	v_pk_mul_f32 v[20:21], v[20:21], v[38:39] op_sel_hi:[1,0]
	v_pk_mul_f32 v[18:19], v[18:19], v[38:39] op_sel_hi:[1,0]
	v_mul_f32_e32 v144, v144, v38
	v_mov_b32_e32 v35, v34
	v_mov_b32_e32 v36, v34
	v_mov_b32_e32 v37, v34
	v_mov_b32_e32 v38, v34
	v_mov_b32_e32 v39, v34
	v_mov_b32_e32 v40, v34
	v_mov_b32_e32 v41, v34
	v_mov_b32_e32 v42, v34
	v_mov_b32_e32 v43, v34
	v_mov_b32_e32 v44, v34
	v_mov_b32_e32 v45, v34
	v_mov_b32_e32 v46, v34
	v_mov_b32_e32 v47, v34
	v_mov_b32_e32 v48, v34
	v_mov_b32_e32 v49, v34
	v_mov_b32_e32 v50, v34
	v_mov_b32_e32 v51, v34
	v_mov_b32_e32 v52, v34
	v_mov_b32_e32 v53, v34
	v_mov_b32_e32 v54, v34
	v_mov_b32_e32 v55, v34
	v_mov_b32_e32 v56, v34
	v_mov_b32_e32 v57, v34
	v_mov_b32_e32 v58, v34
	v_mov_b32_e32 v59, v34
	v_mov_b32_e32 v60, v34
	v_mov_b32_e32 v61, v34
	v_mov_b32_e32 v62, v34
	v_mov_b32_e32 v63, v34
	v_mov_b32_e32 v64, v34
	v_mov_b32_e32 v65, v34
	s_branch .LBB0_607
; template <int DQK, int DV, bool BIAS> ...
;     ...
;         const LAS unsigned char* kb = lds + buf * KBUF + r32 * KP + hi * 16;
; #pragma unroll
;         for (int ks = 0; ks < NKS; ++ks) {
;             const bf16x8 k0 = *(const LAS bf16x8*)(kb + ks * 32), k1 = *(const LAS bf16x8*)(kb + 32 * KP + ks * 32);
;             if (ks == 0) { p0 = __builtin_amdgcn_mfma_f32_32x32x16_bf16(k0, qf[0], negm, 0, 0, 0); p1 = __builtin_amdgcn_mfma_f32_32x32x16_bf16(k1, qf[0], negm, 0, 0, 0); }
;             else { p0 = __builtin_amdgcn_mfma_f32_32x32x16_bf16(k0, qf[ks], p0, 0, 0, 0); p1 = __builtin_amdgcn_mfma_f32_32x32x16_bf16(k1, qf[ks], p1, 0, 0, 0); }
;         }
;         if (BIAS) {
;             asm volatile("s_nop 15\n\ts_nop 7" : "+v"(p0), "+v"(p1));
;             const float d0 = qp - (float)(t * 64 + 4 * hi);
; #pragma unroll
;             for (int r = 0; r < 16; ++r) { const float dk = d0 - (float)((r & 3) + 8 * (r >> 2)); p0[r] = p0[r] - sl2 * fabsf(dk); p1[r] = p1[r] - sl2 * fabsf(dk - 32.f); }
;         } else {
;             asm volatile("s_nop 15\n\ts_nop 7" : "+v"(p0), "+v"(p1));
;         }
;     ...
;         if (!isY) {
;             const LAS unsigned char* vbase = lds + VOFF + vcur * VBUF + (4 * hi + ((lane & 15) >> 2)) * 64 + ((lane >> 4) & 1) * 32 + (lane & 3) * 8;
;             float ls = 0.f;
; #pragma unroll
;             for (int hs = 0; hs < 4; ++hs) {
;                 float e[8];
; #pragma unroll
;                 for (int j = 0; j < 8; ++j) { e[j] = __builtin_amdgcn_exp2f(hs < 2 ? p0[8 * (hs & 1) + j] : p1[8 * (hs & 1) + j]); ls += e[j]; }
;                 pw[hs].x = cvtpk(e[0], e[1]); pw[hs].y = cvtpk(e[2], e[3]); pw[hs].z = cvtpk(e[4], e[5]); pw[hs].w = cvtpk(e[6], e[7]);
;                 const bf16x8 pbv = __builtin_bit_cast(bf16x8, pw[hs]);
; #pragma unroll
;                 for (int d = 0; d < NDT; ++d) { const LAS unsigned char* vp = vbase + d * 4096 + hs * 1024;
;                     const v4i16_t a0 = __builtin_amdgcn_ds_read_tr16_b64_v4i16((LAS v4i16_t*)vp), a1 = __builtin_amdgcn_ds_read_tr16_b64_v4i16((LAS v4i16_t*)(vp + 512));
;                     const bf16x8 av = {a0[0], a0[1], a0[2], a0[3], a1[0], a1[1], a1[2], a1[3]};
;                     o[d] = __builtin_amdgcn_mfma_f32_32x32x16_bf16(av, pbv, o[d], 0, 0, 0); }
;                 __builtin_amdgcn_sched_barrier(0);
;             }
;             l += ls;
.LBB0_606:
.LBB0_607:
	v_exp_f32_e32 v145, v82
	v_exp_f32_e32 v147, v83
	v_exp_f32_e32 v152, v84
	v_exp_f32_e32 v153, v85
	v_exp_f32_e32 v154, v86
	v_exp_f32_e32 v155, v87
	ds_read_b64_tr_b16 v[82:83], v141 offset:36864
	ds_read_b64_tr_b16 v[84:85], v141 offset:37376
	v_exp_f32_e32 v156, v88
	v_exp_f32_e32 v157, v89
	ds_read_b64_tr_b16 v[148:149], v141 offset:40960
	ds_read_b64_tr_b16 v[150:151], v141 offset:41472
	v_cvt_pk_bf16_f32 v86, v145, v147
	v_cvt_pk_bf16_f32 v87, v152, v153
	v_cvt_pk_bf16_f32 v88, v154, v155
	v_cvt_pk_bf16_f32 v89, v156, v157
	s_waitcnt lgkmcnt(2)
	s_nop 0
	v_mfma_f32_32x32x16_bf16 v[18:33], v[82:85], v[86:89], v[18:33]
	v_add_f32_e32 v82, v147, v145
	v_add_f32_e32 v82, v152, v82
	v_add_f32_e32 v82, v153, v82
	v_add_f32_e32 v82, v154, v82
	v_add_f32_e32 v82, v155, v82
	v_add_f32_e32 v82, v156, v82
	s_waitcnt lgkmcnt(0)
	v_mfma_f32_32x32x16_bf16 v[2:17], v[148:151], v[86:89], v[2:17]
	v_add_f32_e32 v145, v157, v82
	v_exp_f32_e32 v147, v90
	v_exp_f32_e32 v148, v91
	v_exp_f32_e32 v149, v92
	v_exp_f32_e32 v150, v93
	v_exp_f32_e32 v94, v94
	v_exp_f32_e32 v95, v95
	ds_read_b64_tr_b16 v[82:83], v141 offset:37888
	ds_read_b64_tr_b16 v[84:85], v141 offset:38400
	v_exp_f32_e32 v96, v96
	v_exp_f32_e32 v97, v97
	ds_read_b64_tr_b16 v[90:91], v141 offset:41984
	ds_read_b64_tr_b16 v[92:93], v141 offset:42496
	v_cvt_pk_bf16_f32 v86, v147, v148
	v_cvt_pk_bf16_f32 v87, v149, v150
	v_cvt_pk_bf16_f32 v88, v94, v95
	v_cvt_pk_bf16_f32 v89, v96, v97
	s_waitcnt lgkmcnt(2)
	s_nop 0
	v_mfma_f32_32x32x16_bf16 v[18:33], v[82:85], v[86:89], v[18:33]
	v_add_f32_e32 v82, v147, v145
	v_add_f32_e32 v82, v148, v82
	v_add_f32_e32 v82, v149, v82
	v_add_f32_e32 v82, v150, v82
	v_add_f32_e32 v82, v94, v82
	v_add_f32_e32 v82, v95, v82
	v_add_f32_e32 v82, v96, v82
	s_waitcnt lgkmcnt(0)
	v_mfma_f32_32x32x16_bf16 v[2:17], v[90:93], v[86:89], v[2:17]
	v_add_f32_e32 v86, v97, v82
	v_exp_f32_e32 v87, v66
	v_exp_f32_e32 v88, v67
	v_exp_f32_e32 v89, v68
	v_exp_f32_e32 v90, v69
	v_exp_f32_e32 v91, v70
	v_exp_f32_e32 v92, v71
	ds_read_b64_tr_b16 v[66:67], v141 offset:38912
	ds_read_b64_tr_b16 v[68:69], v141 offset:39424
	v_exp_f32_e32 v93, v72
	v_exp_f32_e32 v94, v73
	ds_read_b64_tr_b16 v[82:83], v141 offset:43008
	ds_read_b64_tr_b16 v[84:85], v141 offset:43520
	v_cvt_pk_bf16_f32 v70, v87, v88
	v_cvt_pk_bf16_f32 v71, v89, v90
	v_cvt_pk_bf16_f32 v72, v91, v92
	v_cvt_pk_bf16_f32 v73, v93, v94
	s_waitcnt lgkmcnt(2)
	s_nop 0
	v_mfma_f32_32x32x16_bf16 v[18:33], v[66:69], v[70:73], v[18:33]
	v_add_f32_e32 v66, v87, v86
	v_add_f32_e32 v66, v88, v66
	v_add_f32_e32 v66, v89, v66
	v_add_f32_e32 v66, v90, v66
	v_add_f32_e32 v66, v91, v66
	v_add_f32_e32 v66, v92, v66
	v_add_f32_e32 v66, v93, v66
	s_waitcnt lgkmcnt(0)
	v_mfma_f32_32x32x16_bf16 v[2:17], v[82:85], v[70:73], v[2:17]
	v_add_f32_e32 v82, v94, v66
	v_exp_f32_e32 v83, v74
	v_exp_f32_e32 v84, v75
	v_exp_f32_e32 v85, v76
	v_exp_f32_e32 v86, v77
	v_exp_f32_e32 v78, v78
	v_exp_f32_e32 v79, v79
	ds_read_b64_tr_b16 v[66:67], v141 offset:39936
	ds_read_b64_tr_b16 v[68:69], v141 offset:40448
	v_exp_f32_e32 v80, v80
	v_exp_f32_e32 v81, v81
	ds_read_b64_tr_b16 v[74:75], v141 offset:44032
	ds_read_b64_tr_b16 v[76:77], v141 offset:44544
	v_cvt_pk_bf16_f32 v70, v83, v84
	v_cvt_pk_bf16_f32 v71, v85, v86
	v_cvt_pk_bf16_f32 v72, v78, v79
	v_cvt_pk_bf16_f32 v73, v80, v81
	s_waitcnt lgkmcnt(2)
	s_nop 0
	v_mfma_f32_32x32x16_bf16 v[18:33], v[66:69], v[70:73], v[18:33]
	v_add_f32_e32 v66, v83, v82
	v_add_f32_e32 v66, v84, v66
	v_add_f32_e32 v66, v85, v66
	v_add_f32_e32 v66, v86, v66
	v_add_f32_e32 v66, v78, v66
	v_add_f32_e32 v66, v79, v66
	v_add_f32_e32 v66, v80, v66
	s_waitcnt lgkmcnt(0)
	v_mfma_f32_32x32x16_bf16 v[2:17], v[74:77], v[70:73], v[2:17]
	v_add_f32_e32 v145, v81, v66
	ds_read_b128 v[66:69], v130 offset:9216
	ds_read_b128 v[148:151], v130 offset:9248
	ds_read_b128 v[152:155], v130 offset:13824
	ds_read_b128 v[156:159], v130 offset:13856
	v_add_f32_e32 v144, v144, v145
	s_waitcnt lgkmcnt(3)
	v_mfma_f32_32x32x16_bf16 v[82:97], v[66:69], v[98:101], v[34:49]
	s_waitcnt lgkmcnt(1)
	v_mfma_f32_32x32x16_bf16 v[66:81], v[152:155], v[98:101], v[34:49]
	v_mfma_f32_32x32x16_bf16 v[82:97], v[148:151], v[102:105], v[82:97]
	ds_read_b128 v[148:151], v130 offset:9280
	ds_read_b128 v[152:155], v130 offset:9312
	s_waitcnt lgkmcnt(2)
	v_mfma_f32_32x32x16_bf16 v[66:81], v[156:159], v[102:105], v[66:81]
	s_waitcnt lgkmcnt(1)
	v_mfma_f32_32x32x16_bf16 v[82:97], v[148:151], v[106:109], v[82:97]
	ds_read_b128 v[148:151], v130 offset:13888
	ds_read_b128 v[156:159], v130 offset:13920
	s_waitcnt lgkmcnt(1)
	v_mfma_f32_32x32x16_bf16 v[66:81], v[148:151], v[106:109], v[66:81]
	v_mfma_f32_32x32x16_bf16 v[82:97], v[152:155], v[110:113], v[82:97]
	s_waitcnt lgkmcnt(0)
	v_mfma_f32_32x32x16_bf16 v[66:81], v[156:159], v[110:113], v[66:81]
	s_nop 15
	s_nop 7
	s_nop 0
	v_max3_f32 v145, v82, v83, v66
	v_max3_f32 v147, v84, v85, v67
	v_max3_f32 v145, v145, v68, v69
	v_max3_f32 v147, v147, v88, v89
	v_max3_f32 v145, v145, v86, v87
	v_max3_f32 v147, v147, v72, v73
	v_max3_f32 v145, v145, v70, v71
	v_max3_f32 v147, v147, v92, v93
	v_max3_f32 v145, v145, v90, v91
	v_max3_f32 v147, v147, v76, v77
	v_max3_f32 v145, v145, v74, v75
	v_max3_f32 v147, v147, v96, v97
	v_max3_f32 v145, v145, v94, v95
	v_max3_f32 v147, v147, v80, v81
	v_max3_f32 v145, v145, v78, v79
	v_max_f32_e32 v145, v145, v147
	v_cmp_lt_f32_e32 vcc, s47, v145
	s_cbranch_vccz .LBB0_609
; template <int DQK, int DV, bool BIAS> ...
;     ...
;         if (__any(mx > 8.f)) {
;             mx = fmaxf(mx, __shfl_xor(mx, 32));
;             const float dl = fmaxf(mx, 0.f); mhat += dl;
;             const float f = __builtin_amdgcn_exp2f(-dl);
; #pragma unroll
;             for (int r = 0; r < 16; ++r) { p0[r] -= dl; p1[r] -= dl; negm[r] = -mhat; }
;             l *= f;
; #pragma unroll
;             for (int d = 0; d < NDT; ++d)
; #pragma unroll
;                 for (int r = 0; r < 16; ++r) o[d][r] *= f;
;         }
	ds_bpermute_b32 v34, v168, v145
	s_waitcnt lgkmcnt(0)
	v_max3_f32 v36, v145, v34, 0
	v_exp_f32_e64 v38, -v36
	v_add_f32_e32 v143, v143, v36
	v_xor_b32_e32 v34, 0x80000000, v143
	v_pk_add_f32 v[82:83], v[82:83], v[36:37] op_sel_hi:[1,0] neg_lo:[0,1] neg_hi:[0,1]
	v_pk_add_f32 v[66:67], v[66:67], v[36:37] op_sel_hi:[1,0] neg_lo:[0,1] neg_hi:[0,1]
	v_pk_add_f32 v[84:85], v[84:85], v[36:37] op_sel_hi:[1,0] neg_lo:[0,1] neg_hi:[0,1]
	v_pk_add_f32 v[68:69], v[68:69], v[36:37] op_sel_hi:[1,0] neg_lo:[0,1] neg_hi:[0,1]
	v_pk_add_f32 v[86:87], v[86:87], v[36:37] op_sel_hi:[1,0] neg_lo:[0,1] neg_hi:[0,1]
	v_pk_add_f32 v[70:71], v[70:71], v[36:37] op_sel_hi:[1,0] neg_lo:[0,1] neg_hi:[0,1]
	v_pk_add_f32 v[88:89], v[88:89], v[36:37] op_sel_hi:[1,0] neg_lo:[0,1] neg_hi:[0,1]
	v_pk_add_f32 v[72:73], v[72:73], v[36:37] op_sel_hi:[1,0] neg_lo:[0,1] neg_hi:[0,1]
	v_pk_add_f32 v[90:91], v[90:91], v[36:37] op_sel_hi:[1,0] neg_lo:[0,1] neg_hi:[0,1]
	v_pk_add_f32 v[74:75], v[74:75], v[36:37] op_sel_hi:[1,0] neg_lo:[0,1] neg_hi:[0,1]
	v_pk_add_f32 v[92:93], v[92:93], v[36:37] op_sel_hi:[1,0] neg_lo:[0,1] neg_hi:[0,1]
	v_pk_add_f32 v[76:77], v[76:77], v[36:37] op_sel_hi:[1,0] neg_lo:[0,1] neg_hi:[0,1]
	v_pk_add_f32 v[94:95], v[94:95], v[36:37] op_sel_hi:[1,0] neg_lo:[0,1] neg_hi:[0,1]
	v_pk_add_f32 v[78:79], v[78:79], v[36:37] op_sel_hi:[1,0] neg_lo:[0,1] neg_hi:[0,1]
	v_pk_add_f32 v[96:97], v[96:97], v[36:37] op_sel_hi:[1,0] neg_lo:[0,1] neg_hi:[0,1]
	v_pk_add_f32 v[80:81], v[80:81], v[36:37] op_sel_hi:[1,0] neg_lo:[0,1] neg_hi:[0,1]
	v_pk_mul_f32 v[16:17], v[16:17], v[38:39] op_sel_hi:[1,0]
	v_pk_mul_f32 v[14:15], v[14:15], v[38:39] op_sel_hi:[1,0]
	v_pk_mul_f32 v[12:13], v[12:13], v[38:39] op_sel_hi:[1,0]
	v_pk_mul_f32 v[10:11], v[10:11], v[38:39] op_sel_hi:[1,0]
	v_pk_mul_f32 v[8:9], v[8:9], v[38:39] op_sel_hi:[1,0]
	v_pk_mul_f32 v[6:7], v[6:7], v[38:39] op_sel_hi:[1,0]
	v_pk_mul_f32 v[4:5], v[4:5], v[38:39] op_sel_hi:[1,0]
	v_pk_mul_f32 v[2:3], v[2:3], v[38:39] op_sel_hi:[1,0]
	v_pk_mul_f32 v[32:33], v[32:33], v[38:39] op_sel_hi:[1,0]
	v_pk_mul_f32 v[30:31], v[30:31], v[38:39] op_sel_hi:[1,0]
	v_pk_mul_f32 v[28:29], v[28:29], v[38:39] op_sel_hi:[1,0]
	v_pk_mul_f32 v[26:27], v[26:27], v[38:39] op_sel_hi:[1,0]
	v_pk_mul_f32 v[24:25], v[24:25], v[38:39] op_sel_hi:[1,0]
	v_pk_mul_f32 v[22:23], v[22:23], v[38:39] op_sel_hi:[1,0]
	v_pk_mul_f32 v[20:21], v[20:21], v[38:39] op_sel_hi:[1,0]
	v_pk_mul_f32 v[18:19], v[18:19], v[38:39] op_sel_hi:[1,0]
	v_mul_f32_e32 v144, v144, v38
	v_mov_b32_e32 v35, v34
	v_mov_b32_e32 v36, v34
	v_mov_b32_e32 v37, v34
	v_mov_b32_e32 v38, v34
	v_mov_b32_e32 v39, v34
	v_mov_b32_e32 v40, v34
	v_mov_b32_e32 v41, v34
	v_mov_b32_e32 v42, v34
	v_mov_b32_e32 v43, v34
	v_mov_b32_e32 v44, v34
	v_mov_b32_e32 v45, v34
	v_mov_b32_e32 v46, v34
	v_mov_b32_e32 v47, v34
	v_mov_b32_e32 v48, v34
	v_mov_b32_e32 v49, v34
	v_mov_b32_e32 v50, v34
	v_mov_b32_e32 v51, v34
	v_mov_b32_e32 v52, v34
	v_mov_b32_e32 v53, v34
	v_mov_b32_e32 v54, v34
	v_mov_b32_e32 v55, v34
	v_mov_b32_e32 v56, v34
	v_mov_b32_e32 v57, v34
	v_mov_b32_e32 v58, v34
	v_mov_b32_e32 v59, v34
	v_mov_b32_e32 v60, v34
	v_mov_b32_e32 v61, v34
	v_mov_b32_e32 v62, v34
	v_mov_b32_e32 v63, v34
	v_mov_b32_e32 v64, v34
	v_mov_b32_e32 v65, v34

; template <int DQK, int DV, bool BIAS> ...
;     ...
;         const LAS unsigned char* kb = lds + buf * KBUF + r32 * KP + hi * 16;
; #pragma unroll
;         for (int ks = 0; ks < NKS; ++ks) {
;             const bf16x8 k0 = *(const LAS bf16x8*)(kb + ks * 32), k1 = *(const LAS bf16x8*)(kb + 32 * KP + ks * 32);
;             if (ks == 0) { p0 = __builtin_amdgcn_mfma_f32_32x32x16_bf16(k0, qf[0], negm, 0, 0, 0); p1 = __builtin_amdgcn_mfma_f32_32x32x16_bf16(k1, qf[0], negm, 0, 0, 0); }
;             else { p0 = __builtin_amdgcn_mfma_f32_32x32x16_bf16(k0, qf[ks], p0, 0, 0, 0); p1 = __builtin_amdgcn_mfma_f32_32x32x16_bf16(k1, qf[ks], p1, 0, 0, 0); }
;         }
;         if (BIAS) {
;             asm volatile("s_nop 15\n\ts_nop 7" : "+v"(p0), "+v"(p1));
;             const float d0 = qp - (float)(t * 64 + 4 * hi);
; #pragma unroll
;             for (int r = 0; r < 16; ++r) { const float dk = d0 - (float)((r & 3) + 8 * (r >> 2)); p0[r] = p0[r] - sl2 * fabsf(dk); p1[r] = p1[r] - sl2 * fabsf(dk - 32.f); }
;         } else {
;             asm volatile("s_nop 15\n\ts_nop 7" : "+v"(p0), "+v"(p1));
;         }
;     ...
;         if (!isY) {
;             const LAS unsigned char* vbase = lds + VOFF + vcur * VBUF + (4 * hi + ((lane & 15) >> 2)) * 64 + ((lane >> 4) & 1) * 32 + (lane & 3) * 8;
;             float ls = 0.f;
; #pragma unroll
;             for (int hs = 0; hs < 4; ++hs) {
;                 float e[8];
; #pragma unroll
;                 for (int j = 0; j < 8; ++j) { e[j] = __builtin_amdgcn_exp2f(hs < 2 ? p0[8 * (hs & 1) + j] : p1[8 * (hs & 1) + j]); ls += e[j]; }
;                 pw[hs].x = cvtpk(e[0], e[1]); pw[hs].y = cvtpk(e[2], e[3]); pw[hs].z = cvtpk(e[4], e[5]); pw[hs].w = cvtpk(e[6], e[7]);
;                 const bf16x8 pbv = __builtin_bit_cast(bf16x8, pw[hs]);
; #pragma unroll
;                 for (int d = 0; d < NDT; ++d) { const LAS unsigned char* vp = vbase + d * 4096 + hs * 1024;
;                     const v4i16_t a0 = __builtin_amdgcn_ds_read_tr16_b64_v4i16((LAS v4i16_t*)vp), a1 = __builtin_amdgcn_ds_read_tr16_b64_v4i16((LAS v4i16_t*)(vp + 512));
;                     const bf16x8 av = {a0[0], a0[1], a0[2], a0[3], a1[0], a1[1], a1[2], a1[3]};
;                     o[d] = __builtin_amdgcn_mfma_f32_32x32x16_bf16(av, pbv, o[d], 0, 0, 0); }
;                 __builtin_amdgcn_sched_barrier(0);
;             }
;             l += ls;
.LBB0_614:
	v_exp_f32_e32 v145, v82
	v_exp_f32_e32 v147, v83
	v_exp_f32_e32 v152, v84
	v_exp_f32_e32 v153, v85
	v_exp_f32_e32 v154, v86
	v_exp_f32_e32 v155, v87
	ds_read_b64_tr_b16 v[82:83], v141 offset:53248
	ds_read_b64_tr_b16 v[84:85], v141 offset:53760
	v_exp_f32_e32 v156, v88
	v_exp_f32_e32 v157, v89
	ds_read_b64_tr_b16 v[148:149], v141 offset:57344
	ds_read_b64_tr_b16 v[150:151], v141 offset:57856
	v_cvt_pk_bf16_f32 v86, v145, v147
	v_cvt_pk_bf16_f32 v87, v152, v153
	v_cvt_pk_bf16_f32 v88, v154, v155
	v_cvt_pk_bf16_f32 v89, v156, v157
	s_waitcnt lgkmcnt(2)
	s_nop 0
	v_mfma_f32_32x32x16_bf16 v[18:33], v[82:85], v[86:89], v[18:33]
	v_add_f32_e32 v82, v147, v145
	v_add_f32_e32 v82, v152, v82
	v_add_f32_e32 v82, v153, v82
	v_add_f32_e32 v82, v154, v82
	v_add_f32_e32 v82, v155, v82
	v_add_f32_e32 v82, v156, v82
	s_waitcnt lgkmcnt(0)
	v_mfma_f32_32x32x16_bf16 v[2:17], v[148:151], v[86:89], v[2:17]
	v_add_f32_e32 v145, v157, v82
	v_exp_f32_e32 v147, v90
	v_exp_f32_e32 v148, v91
	v_exp_f32_e32 v149, v92
	v_exp_f32_e32 v150, v93
	v_exp_f32_e32 v94, v94
	v_exp_f32_e32 v95, v95
	ds_read_b64_tr_b16 v[82:83], v141 offset:54272
	ds_read_b64_tr_b16 v[84:85], v141 offset:54784
	v_exp_f32_e32 v96, v96
	v_exp_f32_e32 v97, v97
	ds_read_b64_tr_b16 v[90:91], v141 offset:58368
	ds_read_b64_tr_b16 v[92:93], v141 offset:58880
	v_cvt_pk_bf16_f32 v86, v147, v148
	v_cvt_pk_bf16_f32 v87, v149, v150
	v_cvt_pk_bf16_f32 v88, v94, v95
	v_cvt_pk_bf16_f32 v89, v96, v97
	s_waitcnt lgkmcnt(2)
	s_nop 0
	v_mfma_f32_32x32x16_bf16 v[18:33], v[82:85], v[86:89], v[18:33]
	v_add_f32_e32 v82, v147, v145
	v_add_f32_e32 v82, v148, v82
	v_add_f32_e32 v82, v149, v82
	v_add_f32_e32 v82, v150, v82
	v_add_f32_e32 v82, v94, v82
	v_add_f32_e32 v82, v95, v82
	v_add_f32_e32 v82, v96, v82
	s_waitcnt lgkmcnt(0)
	v_mfma_f32_32x32x16_bf16 v[2:17], v[90:93], v[86:89], v[2:17]
	v_add_f32_e32 v86, v97, v82
	v_exp_f32_e32 v87, v66
	v_exp_f32_e32 v88, v67
	v_exp_f32_e32 v89, v68
	v_exp_f32_e32 v90, v69
	v_exp_f32_e32 v91, v70
	v_exp_f32_e32 v92, v71
	ds_read_b64_tr_b16 v[66:67], v141 offset:55296
	ds_read_b64_tr_b16 v[68:69], v141 offset:55808
	v_exp_f32_e32 v93, v72
	v_exp_f32_e32 v94, v73
	ds_read_b64_tr_b16 v[82:83], v141 offset:59392
	ds_read_b64_tr_b16 v[84:85], v141 offset:59904
	v_cvt_pk_bf16_f32 v70, v87, v88
	v_cvt_pk_bf16_f32 v71, v89, v90
	v_cvt_pk_bf16_f32 v72, v91, v92
	v_cvt_pk_bf16_f32 v73, v93, v94
	s_waitcnt lgkmcnt(2)
	s_nop 0
	v_mfma_f32_32x32x16_bf16 v[18:33], v[66:69], v[70:73], v[18:33]
	v_add_f32_e32 v66, v87, v86
	v_add_f32_e32 v66, v88, v66
	v_add_f32_e32 v66, v89, v66
	v_add_f32_e32 v66, v90, v66
	v_add_f32_e32 v66, v91, v66
	v_add_f32_e32 v66, v92, v66
	v_add_f32_e32 v66, v93, v66
	s_waitcnt lgkmcnt(0)
	v_mfma_f32_32x32x16_bf16 v[2:17], v[82:85], v[70:73], v[2:17]
	v_add_f32_e32 v82, v94, v66
	v_exp_f32_e32 v83, v74
	v_exp_f32_e32 v84, v75
	v_exp_f32_e32 v85, v76
	v_exp_f32_e32 v86, v77
	v_exp_f32_e32 v78, v78
	v_exp_f32_e32 v79, v79
	ds_read_b64_tr_b16 v[66:67], v141 offset:56320
	ds_read_b64_tr_b16 v[68:69], v141 offset:56832
	v_exp_f32_e32 v80, v80
	v_exp_f32_e32 v81, v81
	ds_read_b64_tr_b16 v[74:75], v141 offset:60416
	ds_read_b64_tr_b16 v[76:77], v141 offset:60928
	v_cvt_pk_bf16_f32 v70, v83, v84
	v_cvt_pk_bf16_f32 v71, v85, v86
	v_cvt_pk_bf16_f32 v72, v78, v79
	v_cvt_pk_bf16_f32 v73, v80, v81
	s_waitcnt lgkmcnt(2)
	s_nop 0
	v_mfma_f32_32x32x16_bf16 v[18:33], v[66:69], v[70:73], v[18:33]
	v_add_f32_e32 v66, v83, v82
	v_add_f32_e32 v66, v84, v66
	v_add_f32_e32 v66, v85, v66
	v_add_f32_e32 v66, v86, v66
	v_add_f32_e32 v66, v78, v66
	v_add_f32_e32 v66, v79, v66
	v_add_f32_e32 v66, v80, v66
	s_waitcnt lgkmcnt(0)
	v_mfma_f32_32x32x16_bf16 v[2:17], v[74:77], v[70:73], v[2:17]
	v_add_f32_e32 v94, v81, v66
	ds_read_b128 v[82:85], v130 offset:27648
	ds_read_b128 v[86:89], v130 offset:27680
	s_waitcnt lgkmcnt(1)
	v_mfma_f32_32x32x16_bf16 v[66:81], v[82:85], v[98:101], v[34:49]
	ds_read_b128 v[82:85], v130 offset:32256
	ds_read_b128 v[90:93], v130 offset:32288
	s_waitcnt lgkmcnt(1)
	v_mfma_f32_32x32x16_bf16 v[208:223], v[82:85], v[98:101], v[34:49]
	v_mfma_f32_32x32x16_bf16 v[66:81], v[86:89], v[102:105], v[66:81]
	ds_read_b128 v[82:85], v130 offset:27712
	ds_read_b128 v[86:89], v130 offset:27744
	s_waitcnt lgkmcnt(2)
	v_mfma_f32_32x32x16_bf16 v[208:223], v[90:93], v[102:105], v[208:223]
	s_waitcnt lgkmcnt(1)
	v_mfma_f32_32x32x16_bf16 v[66:81], v[82:85], v[106:109], v[66:81]
	ds_read_b128 v[82:85], v130 offset:32320
	ds_read_b128 v[90:93], v130 offset:32352
	s_waitcnt lgkmcnt(1)
	v_mfma_f32_32x32x16_bf16 v[208:223], v[82:85], v[106:109], v[208:223]
	v_add_f32_e32 v82, v144, v94
	v_mfma_f32_32x32x16_bf16 v[66:81], v[86:89], v[110:113], v[66:81]
	s_waitcnt lgkmcnt(0)
	v_mfma_f32_32x32x16_bf16 v[208:223], v[90:93], v[110:113], v[208:223]
	s_nop 15
	s_nop 7
	s_nop 0
	v_max3_f32 v83, v66, v67, v208
	v_max3_f32 v84, v68, v69, v209
	v_max3_f32 v83, v83, v210, v211
	v_max3_f32 v84, v84, v72, v73
	v_max3_f32 v83, v83, v70, v71
	v_max3_f32 v84, v84, v214, v215
	v_max3_f32 v83, v83, v212, v213
	v_max3_f32 v84, v84, v76, v77
	v_max3_f32 v83, v83, v74, v75
	v_max3_f32 v84, v84, v218, v219
	v_max3_f32 v83, v83, v216, v217
	v_max3_f32 v84, v84, v80, v81
	v_max3_f32 v83, v83, v78, v79
	v_max3_f32 v84, v84, v222, v223
	v_max3_f32 v83, v83, v220, v221
	v_max_f32_e32 v83, v83, v84
	v_cmp_lt_f32_e32 vcc, s47, v83
	s_cbranch_vccz .LBB0_601
; template <int DQK, int DV, bool BIAS> ...
;     ...
;         if (__any(mx > 8.f)) {
;             mx = fmaxf(mx, __shfl_xor(mx, 32));
;             const float dl = fmaxf(mx, 0.f); mhat += dl;
;             const float f = __builtin_amdgcn_exp2f(-dl);
; #pragma unroll
;             for (int r = 0; r < 16; ++r) { p0[r] -= dl; p1[r] -= dl; negm[r] = -mhat; }
;             l *= f;
; #pragma unroll
;             for (int d = 0; d < NDT; ++d)
; #pragma unroll
;                 for (int r = 0; r < 16; ++r) o[d][r] *= f;
;         }
	ds_bpermute_b32 v50, v168, v83
	s_waitcnt lgkmcnt(0)
	v_max3_f32 v52, v83, v50, 0
	v_exp_f32_e64 v54, -v52
	v_add_f32_e32 v143, v143, v52
	v_xor_b32_e32 v50, 0x80000000, v143
	v_pk_add_f32 v[66:67], v[66:67], v[52:53] op_sel_hi:[1,0] neg_lo:[0,1] neg_hi:[0,1]
	v_pk_add_f32 v[208:209], v[208:209], v[52:53] op_sel_hi:[1,0] neg_lo:[0,1] neg_hi:[0,1]
	v_pk_add_f32 v[68:69], v[68:69], v[52:53] op_sel_hi:[1,0] neg_lo:[0,1] neg_hi:[0,1]
	v_pk_add_f32 v[210:211], v[210:211], v[52:53] op_sel_hi:[1,0] neg_lo:[0,1] neg_hi:[0,1]
	v_pk_add_f32 v[70:71], v[70:71], v[52:53] op_sel_hi:[1,0] neg_lo:[0,1] neg_hi:[0,1]
	v_pk_add_f32 v[212:213], v[212:213], v[52:53] op_sel_hi:[1,0] neg_lo:[0,1] neg_hi:[0,1]
	v_pk_add_f32 v[72:73], v[72:73], v[52:53] op_sel_hi:[1,0] neg_lo:[0,1] neg_hi:[0,1]
	v_pk_add_f32 v[214:215], v[214:215], v[52:53] op_sel_hi:[1,0] neg_lo:[0,1] neg_hi:[0,1]
	v_pk_add_f32 v[74:75], v[74:75], v[52:53] op_sel_hi:[1,0] neg_lo:[0,1] neg_hi:[0,1]
	v_pk_add_f32 v[216:217], v[216:217], v[52:53] op_sel_hi:[1,0] neg_lo:[0,1] neg_hi:[0,1]
	v_pk_add_f32 v[76:77], v[76:77], v[52:53] op_sel_hi:[1,0] neg_lo:[0,1] neg_hi:[0,1]
	v_pk_add_f32 v[218:219], v[218:219], v[52:53] op_sel_hi:[1,0] neg_lo:[0,1] neg_hi:[0,1]
	v_pk_add_f32 v[78:79], v[78:79], v[52:53] op_sel_hi:[1,0] neg_lo:[0,1] neg_hi:[0,1]
	v_pk_add_f32 v[220:221], v[220:221], v[52:53] op_sel_hi:[1,0] neg_lo:[0,1] neg_hi:[0,1]
	v_pk_add_f32 v[80:81], v[80:81], v[52:53] op_sel_hi:[1,0] neg_lo:[0,1] neg_hi:[0,1]
	v_pk_add_f32 v[222:223], v[222:223], v[52:53] op_sel_hi:[1,0] neg_lo:[0,1] neg_hi:[0,1]
	v_pk_mul_f32 v[16:17], v[16:17], v[54:55] op_sel_hi:[1,0]
	v_pk_mul_f32 v[14:15], v[14:15], v[54:55] op_sel_hi:[1,0]
	v_pk_mul_f32 v[12:13], v[12:13], v[54:55] op_sel_hi:[1,0]
	v_pk_mul_f32 v[10:11], v[10:11], v[54:55] op_sel_hi:[1,0]
	v_pk_mul_f32 v[8:9], v[8:9], v[54:55] op_sel_hi:[1,0]
	v_pk_mul_f32 v[6:7], v[6:7], v[54:55] op_sel_hi:[1,0]
	v_pk_mul_f32 v[4:5], v[4:5], v[54:55] op_sel_hi:[1,0]
	v_pk_mul_f32 v[2:3], v[2:3], v[54:55] op_sel_hi:[1,0]
	v_pk_mul_f32 v[32:33], v[32:33], v[54:55] op_sel_hi:[1,0]
	v_pk_mul_f32 v[30:31], v[30:31], v[54:55] op_sel_hi:[1,0]
	v_pk_mul_f32 v[28:29], v[28:29], v[54:55] op_sel_hi:[1,0]
	v_pk_mul_f32 v[26:27], v[26:27], v[54:55] op_sel_hi:[1,0]
	v_pk_mul_f32 v[24:25], v[24:25], v[54:55] op_sel_hi:[1,0]
	v_pk_mul_f32 v[22:23], v[22:23], v[54:55] op_sel_hi:[1,0]
	v_pk_mul_f32 v[20:21], v[20:21], v[54:55] op_sel_hi:[1,0]
	v_pk_mul_f32 v[18:19], v[18:19], v[54:55] op_sel_hi:[1,0]
	v_mul_f32_e32 v82, v82, v54
	v_mov_b32_e32 v51, v50
	v_mov_b32_e32 v52, v50
	v_mov_b32_e32 v53, v50
	v_mov_b32_e32 v54, v50
	v_mov_b32_e32 v55, v50
	v_mov_b32_e32 v56, v50
	v_mov_b32_e32 v57, v50
	v_mov_b32_e32 v58, v50
	v_mov_b32_e32 v59, v50
	v_mov_b32_e32 v60, v50
	v_mov_b32_e32 v61, v50
	v_mov_b32_e32 v62, v50
	v_mov_b32_e32 v63, v50
	v_mov_b32_e32 v64, v50
	v_mov_b32_e32 v65, v50
	v_mov_b32_e32 v34, v50
	v_mov_b32_e32 v35, v50
	v_mov_b32_e32 v36, v50
	v_mov_b32_e32 v37, v50
	v_mov_b32_e32 v38, v50
	v_mov_b32_e32 v39, v50
	v_mov_b32_e32 v40, v50
	v_mov_b32_e32 v41, v50
	v_mov_b32_e32 v42, v50
	v_mov_b32_e32 v43, v50
	v_mov_b32_e32 v44, v50
	v_mov_b32_e32 v45, v50
	v_mov_b32_e32 v46, v50
	v_mov_b32_e32 v47, v50
	v_mov_b32_e32 v48, v50
	v_mov_b32_e32 v49, v50
	s_branch .LBB0_601

; #define LAS __attribute__((address_space(3)))
; __device__ __forceinline__ unsigned cvtpk(float lo, float hi) { typedef __bf16 bf2 __attribute__((ext_vector_type(2))); f32x2 v = {lo, hi}; bf2 b = __builtin_convertvector(v, bf2); return __builtin_bit_cast(unsigned, b); }
; template <int DQK, int DV, bool BIAS> ...
;     ...
;     const bf16_t* kptr = Kg + (size_t)(tid >> 3) * ldk + (tid & 7) * 8;
;     const bf16_t* k2ptr = (DQK == 96) ? K2g + (size_t)(tid >> 2) * ldk2 + (tid & 3) * 8 : nullptr;
;     ...
;     u32x4 pw[4];
; #pragma unroll
;     for (int j = 0; j < TPB; ++j) { ATT_LOAD(j, j); ATT_STORE(j, j); }
; #pragma unroll
;     for (int j = 0; j < TPB; ++j) ATT_LOAD(TPB + j, j);
;     const float qp = (float)(qpos0 + r32);
;     ...
;         if (!isY) {
;             const LAS unsigned char* vbase = lds + VOFF + vcur * VBUF + (4 * hi + ((lane & 15) >> 2)) * 64 + ((lane >> 4) & 1) * 32 + (lane & 3) * 8;
;             float ls = 0.f;
; #pragma unroll
;             for (int hs = 0; hs < 4; ++hs) {
;                 float e[8];
; #pragma unroll
;                 for (int j = 0; j < 8; ++j) { e[j] = __builtin_amdgcn_exp2f(hs < 2 ? p0[8 * (hs & 1) + j] : p1[8 * (hs & 1) + j]); ls += e[j]; }
;                 pw[hs].x = cvtpk(e[0], e[1]); pw[hs].y = cvtpk(e[2], e[3]); pw[hs].z = cvtpk(e[4], e[5]); pw[hs].w = cvtpk(e[6], e[7]);
;                 const bf16x8 pbv = __builtin_bit_cast(bf16x8, pw[hs]);
; #pragma unroll
;                 for (int d = 0; d < NDT; ++d) { const LAS unsigned char* vp = vbase + d * 4096 + hs * 1024;
;                     const v4i16_t a0 = __builtin_amdgcn_ds_read_tr16_b64_v4i16((LAS v4i16_t*)vp), a1 = __builtin_amdgcn_ds_read_tr16_b64_v4i16((LAS v4i16_t*)(vp + 512));
;                     const bf16x8 av = {a0[0], a0[1], a0[2], a0[3], a1[0], a1[1], a1[2], a1[3]};
;                     o[d] = __builtin_amdgcn_mfma_f32_32x32x16_bf16(av, pbv, o[d], 0, 0, 0); }
;                 __builtin_amdgcn_sched_barrier(0);
;             }
;             l += ls;
.LBB0_630:
	s_or_b64 exec, exec, s[42:43]
	v_add_co_u32_e32 v2, vcc, 0x60000, v22
	s_xor_b64 s[38:39], s[38:39], -1
	s_nop 0
	v_addc_co_u32_e32 v3, vcc, 0, v23, vcc
	global_load_dwordx4 v[142:145], v[2:3], off
	v_mad_i64_i32 v[2:3], s[42:43], v13, s55, 0
	s_add_u32 s40, s52, s40
	v_lshl_add_u64 v[2:3], s[44:45], 0, v[2:3]
	v_mov_b32_e32 v153, v149
	s_addc_u32 s41, 0, s41
	v_lshlrev_b32_e32 v4, 8, v28
	v_and_b32_e32 v5, 0xc0, v30
	v_add_u32_e32 v163, 0, v17
	v_lshl_add_u64 v[154:155], v[2:3], 0, v[152:153]
	v_lshl_add_u64 v[2:3], s[40:41], 0, v[10:11]
	v_mov_b32_e32 v13, v149
	v_mov_b32_e32 v17, v149
	v_add3_u32 v4, 0, v4, v5
	v_lshlrev_b32_e32 v5, 1, v26
	v_lshl_add_u64 v[156:157], v[2:3], 0, v[12:13]
	v_lshl_add_u64 v[2:3], s[40:41], 0, v[16:17]
	v_mad_u32_u24 v18, v27, s58, 0
	v_and_b32_e32 v5, 32, v5
	v_lshl_add_u64 v[2:3], v[2:3], 0, v[152:153]
	v_mov_b32_e32 v16, v149
	v_add3_u32 v161, v4, v5, v29
	v_lshl_add_u64 v[158:159], v[14:15], 1, v[2:3]
	v_mov_b32_e32 v2, v149
	v_mov_b32_e32 v3, v149
	v_mov_b32_e32 v4, v149
	v_mov_b32_e32 v5, v149
	v_mov_b32_e32 v6, v149
	v_mov_b32_e32 v7, v149
	v_mov_b32_e32 v8, v149
	v_mov_b32_e32 v9, v149
	v_mov_b32_e32 v10, v149
	v_mov_b32_e32 v11, v149
	v_mov_b32_e32 v12, v149
	v_mov_b32_e32 v14, v149
	v_mov_b32_e32 v15, v149
	v_mov_b32_e32 v164, 0
	v_add_u32_e32 v148, v18, v148
	v_mov_b64_e32 v[32:33], v[16:17]
	v_add_u32_e32 v160, 0xd000, v151
	s_mov_b32 s46, 0
	v_add_u32_e32 v162, 0xd000, v161
	v_mov_b64_e32 v[30:31], v[14:15]
	v_mov_b64_e32 v[28:29], v[12:13]
	v_mov_b64_e32 v[26:27], v[10:11]
	v_mov_b64_e32 v[24:25], v[8:9]
	v_mov_b64_e32 v[22:23], v[6:7]
	v_mov_b64_e32 v[20:21], v[4:5]
	v_mov_b64_e32 v[18:19], v[2:3]
	v_mov_b32_e32 v153, 0
	v_mov_b32_e32 v50, 0
	v_mov_b32_e32 v51, v164
	v_mov_b32_e32 v52, v164
	v_mov_b32_e32 v53, v164
	v_mov_b32_e32 v54, v164
	v_mov_b32_e32 v55, v164
	v_mov_b32_e32 v56, v164
	v_mov_b32_e32 v57, v164
	v_mov_b32_e32 v58, v164
	v_mov_b32_e32 v59, v164
	v_mov_b32_e32 v60, v164
	v_mov_b32_e32 v61, v164
	v_mov_b32_e32 v62, v164
	v_mov_b32_e32 v63, v164
	v_mov_b32_e32 v64, v164
	v_mov_b32_e32 v65, v164
	v_mov_b32_e32 v34, 0
	v_mov_b32_e32 v35, 0
	v_mov_b32_e32 v36, 0
	v_mov_b32_e32 v37, 0
	v_mov_b32_e32 v38, 0
	v_mov_b32_e32 v39, 0
	v_mov_b32_e32 v40, 0
	v_mov_b32_e32 v41, 0
	v_mov_b32_e32 v42, 0
	v_mov_b32_e32 v43, 0
	v_mov_b32_e32 v44, 0
	v_mov_b32_e32 v45, 0
	v_mov_b32_e32 v46, 0
	v_mov_b32_e32 v47, 0
	v_mov_b32_e32 v48, 0
	v_mov_b32_e32 v49, 0
	s_branch .LBB0_632
.LBB0_631:
	s_nop 4
	v_exp_f32_e32 v83, v66
	v_exp_f32_e32 v88, v67
	v_exp_f32_e32 v89, v68
	v_exp_f32_e32 v90, v69
	v_exp_f32_e32 v91, v70
	v_exp_f32_e32 v92, v71
	ds_read_b64_tr_b16 v[66:67], v162 offset:24576
	ds_read_b64_tr_b16 v[68:69], v162 offset:25088
	v_exp_f32_e32 v93, v72
	v_exp_f32_e32 v94, v73
	ds_read_b64_tr_b16 v[84:85], v162 offset:28672
	ds_read_b64_tr_b16 v[86:87], v162 offset:29184
	v_cvt_pk_bf16_f32 v70, v83, v88
	v_cvt_pk_bf16_f32 v71, v89, v90
	v_cvt_pk_bf16_f32 v72, v91, v92
	v_cvt_pk_bf16_f32 v73, v93, v94
	s_add_i32 s46, s46, 2
	s_waitcnt lgkmcnt(2)
	v_mfma_f32_32x32x16_bf16 v[18:33], v[66:69], v[70:73], v[18:33]
	v_add_f32_e32 v66, v88, v83
	v_add_f32_e32 v66, v89, v66
	v_add_f32_e32 v66, v90, v66
	v_add_f32_e32 v66, v91, v66
	v_add_f32_e32 v66, v92, v66
	v_add_f32_e32 v66, v93, v66
	s_waitcnt lgkmcnt(0)
	v_mfma_f32_32x32x16_bf16 v[2:17], v[84:87], v[70:73], v[2:17]
	v_add_f32_e32 v83, v94, v66
	v_exp_f32_e32 v84, v74
	v_exp_f32_e32 v85, v75
	v_exp_f32_e32 v86, v76
	v_exp_f32_e32 v87, v77
	v_exp_f32_e32 v78, v78
	v_exp_f32_e32 v79, v79
	ds_read_b64_tr_b16 v[66:67], v162 offset:25600
	ds_read_b64_tr_b16 v[68:69], v162 offset:26112
	v_exp_f32_e32 v80, v80
	v_exp_f32_e32 v81, v81
	ds_read_b64_tr_b16 v[74:75], v162 offset:29696
	ds_read_b64_tr_b16 v[76:77], v162 offset:30208
	v_cvt_pk_bf16_f32 v70, v84, v85
	v_cvt_pk_bf16_f32 v71, v86, v87
	v_cvt_pk_bf16_f32 v72, v78, v79
	v_cvt_pk_bf16_f32 v73, v80, v81
	s_waitcnt lgkmcnt(2)
	s_nop 0
	v_mfma_f32_32x32x16_bf16 v[18:33], v[66:69], v[70:73], v[18:33]
	v_add_f32_e32 v66, v84, v83
	v_add_f32_e32 v66, v85, v66
	v_add_f32_e32 v66, v86, v66
	v_add_f32_e32 v66, v87, v66
	v_add_f32_e32 v66, v78, v66
	v_add_f32_e32 v66, v79, v66
	v_add_f32_e32 v66, v80, v66
	s_waitcnt lgkmcnt(0)
	v_mfma_f32_32x32x16_bf16 v[2:17], v[74:77], v[70:73], v[2:17]
	v_add_f32_e32 v70, v81, v66
	v_exp_f32_e32 v71, v208
	v_exp_f32_e32 v72, v209
	v_exp_f32_e32 v73, v210
	v_exp_f32_e32 v74, v211
	v_exp_f32_e32 v75, v212
	v_exp_f32_e32 v76, v213
	ds_read_b64_tr_b16 v[208:209], v162 offset:26624
	ds_read_b64_tr_b16 v[210:211], v162 offset:27136
	v_exp_f32_e32 v77, v214
	v_exp_f32_e32 v78, v215
	ds_read_b64_tr_b16 v[66:67], v162 offset:30720
	ds_read_b64_tr_b16 v[68:69], v162 offset:31232
	v_cvt_pk_bf16_f32 v212, v71, v72
	v_cvt_pk_bf16_f32 v213, v73, v74
	v_cvt_pk_bf16_f32 v214, v75, v76
	v_cvt_pk_bf16_f32 v215, v77, v78
	s_waitcnt lgkmcnt(2)
	s_nop 0
	v_mfma_f32_32x32x16_bf16 v[18:33], v[208:211], v[212:215], v[18:33]
	v_add_f32_e32 v208, v71, v70
	v_add_f32_e32 v208, v72, v208
	v_add_f32_e32 v208, v73, v208
	v_add_f32_e32 v208, v74, v208
	v_add_f32_e32 v208, v75, v208
	v_add_f32_e32 v208, v76, v208
	v_add_f32_e32 v208, v77, v208
	s_waitcnt lgkmcnt(0)
	v_mfma_f32_32x32x16_bf16 v[2:17], v[66:69], v[212:215], v[2:17]
	v_add_f32_e32 v66, v78, v208
	v_exp_f32_e32 v67, v216
	v_exp_f32_e32 v68, v217
	v_exp_f32_e32 v69, v218
	v_exp_f32_e32 v70, v219
	v_exp_f32_e32 v220, v220
	v_exp_f32_e32 v221, v221
	ds_read_b64_tr_b16 v[208:209], v162 offset:27648
	ds_read_b64_tr_b16 v[210:211], v162 offset:28160
	v_exp_f32_e32 v222, v222
	v_exp_f32_e32 v223, v223
	ds_read_b64_tr_b16 v[216:217], v162 offset:31744
	ds_read_b64_tr_b16 v[218:219], v162 offset:32256
	v_cvt_pk_bf16_f32 v212, v67, v68
	v_cvt_pk_bf16_f32 v213, v69, v70
	v_cvt_pk_bf16_f32 v214, v220, v221
	v_cvt_pk_bf16_f32 v215, v222, v223
	s_waitcnt lgkmcnt(2)
	s_nop 0
	v_mfma_f32_32x32x16_bf16 v[18:33], v[208:211], v[212:215], v[18:33]
	v_add_f32_e32 v208, v67, v66
	v_add_f32_e32 v208, v68, v208
	v_add_f32_e32 v208, v69, v208
	v_add_f32_e32 v208, v70, v208
	v_add_f32_e32 v208, v220, v208
	v_add_f32_e32 v208, v221, v208
	v_add_f32_e32 v208, v222, v208
	s_waitcnt lgkmcnt(0)
	v_mfma_f32_32x32x16_bf16 v[2:17], v[216:219], v[212:215], v[2:17]
	v_add_f32_e32 v208, v223, v208
	v_add_f32_e32 v164, v82, v208
	v_lshl_add_u64 v[154:155], v[154:155], 0, s[22:23]
	v_lshl_add_u64 v[156:157], v[156:157], 0, s[34:35]
	s_cmp_lg_u32 s46, 32
	v_lshl_add_u64 v[158:159], v[158:159], 0, s[34:35]
	s_cbranch_scc0 .LBB0_617

; template <int DQK, int DV, bool BIAS> ...
;     ...
;             for (int j = 0; j < TPB; ++j) ATT_STORE((pair ^ 1) * TPB + j, j);
.LBB0_634:
	s_andn2_saveexec_b64 s[40:41], s[40:41]
	s_cbranch_execz .LBB0_636
	v_add_u32_e32 v208, v163, v152
	ds_write_b128 v208, v[122:125] offset:26752
	s_waitcnt vmcnt(2)
	ds_write_b128 v160, v[134:137] offset:16384
	s_waitcnt vmcnt(1)
	ds_write_b128 v147, v[138:141] offset:39936
	ds_write_b128 v208, v[126:129] offset:40064

; #define LAS __attribute__((address_space(3)))
; __device__ __forceinline__ float max3f(float a, float b, float c) { float r; asm("v_max3_f32 %0, %1, %2, %3" : "=v"(r) : "v"(a), "v"(b), "v"(c)); return r; }
; template <int DQK, int DV, bool BIAS> ...
;     ...
;         const LAS unsigned char* kb = lds + buf * KBUF + r32 * KP + hi * 16;
; #pragma unroll
;         for (int ks = 0; ks < NKS; ++ks) {
;             const bf16x8 k0 = *(const LAS bf16x8*)(kb + ks * 32), k1 = *(const LAS bf16x8*)(kb + 32 * KP + ks * 32);
;             if (ks == 0) { p0 = __builtin_amdgcn_mfma_f32_32x32x16_bf16(k0, qf[0], negm, 0, 0, 0); p1 = __builtin_amdgcn_mfma_f32_32x32x16_bf16(k1, qf[0], negm, 0, 0, 0); }
;             else { p0 = __builtin_amdgcn_mfma_f32_32x32x16_bf16(k0, qf[ks], p0, 0, 0, 0); p1 = __builtin_amdgcn_mfma_f32_32x32x16_bf16(k1, qf[ks], p1, 0, 0, 0); }
;         }
;         if (BIAS) {
;             asm volatile("s_nop 15\n\ts_nop 7" : "+v"(p0), "+v"(p1));
;             const float d0 = qp - (float)(t * 64 + 4 * hi);
; #pragma unroll
;             for (int r = 0; r < 16; ++r) { const float dk = d0 - (float)((r & 3) + 8 * (r >> 2)); p0[r] = p0[r] - sl2 * fabsf(dk); p1[r] = p1[r] - sl2 * fabsf(dk - 32.f); }
;         } else {
;             asm volatile("s_nop 15\n\ts_nop 7" : "+v"(p0), "+v"(p1));
;         }
;         float mxa = max3f(p0[0], p0[1], p1[0]), mxb = max3f(p0[2], p0[3], p1[1]); mxa = max3f(mxa, p1[2], p1[3]);
; #pragma unroll
;         for (int r = 4; r < 16; r += 4) { mxa = max3f(mxa, p0[r], p0[r + 1]); mxb = max3f(mxb, p0[r + 2], p0[r + 3]); mxa = max3f(mxa, p1[r], p1[r + 1]); mxb = max3f(mxb, p1[r + 2], p1[r + 3]); }
;         float mx = fmaxf(mxa, mxb);
;         if (__any(mx > 8.f)) {
;             mx = fmaxf(mx, __shfl_xor(mx, 32));
;             const float dl = fmaxf(mx, 0.f); mhat += dl;
;             const float f = __builtin_amdgcn_exp2f(-dl);
; #pragma unroll
;             for (int r = 0; r < 16; ++r) { p0[r] -= dl; p1[r] -= dl; negm[r] = -mhat; }
;             l *= f;
; #pragma unroll
;             for (int d = 0; d < NDT; ++d)
; #pragma unroll
;                 for (int r = 0; r < 16; ++r) o[d][r] *= f;
;         }
.LBB0_642:
	ds_read_b128 v[208:211], v148
	ds_read_b128 v[212:215], v148 offset:32
	s_waitcnt lgkmcnt(1)
	v_mfma_f32_32x32x16_bf16 v[82:97], v[208:211], v[98:101], v[50:65]
	ds_read_b128 v[208:211], v148 offset:6656
	ds_read_b128 v[216:219], v148 offset:6688
	s_waitcnt lgkmcnt(1)
	v_mfma_f32_32x32x16_bf16 v[66:81], v[208:211], v[98:101], v[50:65]
	v_mfma_f32_32x32x16_bf16 v[82:97], v[212:215], v[102:105], v[82:97]
	ds_read_b128 v[208:211], v148 offset:64
	ds_read_b128 v[212:215], v148 offset:96
	s_waitcnt lgkmcnt(2)
	v_mfma_f32_32x32x16_bf16 v[66:81], v[216:219], v[102:105], v[66:81]
	s_waitcnt lgkmcnt(1)
	v_mfma_f32_32x32x16_bf16 v[82:97], v[208:211], v[106:109], v[82:97]
	ds_read_b128 v[208:211], v148 offset:6720
	ds_read_b128 v[216:219], v148 offset:6752
	s_waitcnt lgkmcnt(1)
	v_mfma_f32_32x32x16_bf16 v[66:81], v[208:211], v[106:109], v[66:81]
	v_mfma_f32_32x32x16_bf16 v[82:97], v[212:215], v[110:113], v[82:97]
	ds_read_b128 v[208:211], v148 offset:128
	ds_read_b128 v[212:215], v148 offset:160
	s_waitcnt lgkmcnt(2)
	v_mfma_f32_32x32x16_bf16 v[66:81], v[216:219], v[110:113], v[66:81]
	s_waitcnt lgkmcnt(1)
	v_mfma_f32_32x32x16_bf16 v[82:97], v[208:211], v[114:117], v[82:97]
	ds_read_b128 v[208:211], v148 offset:6784
	ds_read_b128 v[216:219], v148 offset:6816
	s_waitcnt lgkmcnt(1)
	v_mfma_f32_32x32x16_bf16 v[66:81], v[208:211], v[114:117], v[66:81]
	v_mfma_f32_32x32x16_bf16 v[82:97], v[212:215], v[118:121], v[82:97]
	s_waitcnt lgkmcnt(0)
	v_mfma_f32_32x32x16_bf16 v[66:81], v[216:219], v[118:121], v[66:81]
	s_nop 15
	s_nop 7
	s_nop 0
	v_max3_f32 v226, v82, v83, v66
	v_max3_f32 v227, v84, v85, v67
	v_max3_f32 v226, v226, v68, v69
	v_max3_f32 v227, v227, v88, v89
	v_max3_f32 v226, v226, v86, v87
	v_max3_f32 v227, v227, v72, v73
	v_max3_f32 v226, v226, v70, v71
	v_max3_f32 v227, v227, v92, v93
	v_max3_f32 v226, v226, v90, v91
	v_max3_f32 v227, v227, v76, v77
	v_max3_f32 v226, v226, v74, v75
	v_max3_f32 v227, v227, v96, v97
	v_max3_f32 v226, v226, v94, v95
	v_max3_f32 v227, v227, v80, v81
	v_max3_f32 v226, v226, v78, v79
	v_max_f32_e32 v226, v226, v227
	v_cmp_lt_f32_e32 vcc, s59, v226
	s_cbranch_vccz .LBB0_644
	ds_bpermute_b32 v227, v168, v226
	s_waitcnt lgkmcnt(0)
	v_max3_f32 v36, v226, v227, 0
	v_exp_f32_e64 v38, -v36
	v_add_f32_e32 v153, v153, v36
	v_xor_b32_e32 v34, 0x80000000, v153
	v_pk_add_f32 v[82:83], v[82:83], v[36:37] op_sel_hi:[1,0] neg_lo:[0,1] neg_hi:[0,1]
	v_pk_add_f32 v[66:67], v[66:67], v[36:37] op_sel_hi:[1,0] neg_lo:[0,1] neg_hi:[0,1]
	v_pk_add_f32 v[84:85], v[84:85], v[36:37] op_sel_hi:[1,0] neg_lo:[0,1] neg_hi:[0,1]
	v_pk_add_f32 v[68:69], v[68:69], v[36:37] op_sel_hi:[1,0] neg_lo:[0,1] neg_hi:[0,1]
	v_pk_add_f32 v[86:87], v[86:87], v[36:37] op_sel_hi:[1,0] neg_lo:[0,1] neg_hi:[0,1]
	v_pk_add_f32 v[70:71], v[70:71], v[36:37] op_sel_hi:[1,0] neg_lo:[0,1] neg_hi:[0,1]
	v_pk_add_f32 v[88:89], v[88:89], v[36:37] op_sel_hi:[1,0] neg_lo:[0,1] neg_hi:[0,1]
	v_pk_add_f32 v[72:73], v[72:73], v[36:37] op_sel_hi:[1,0] neg_lo:[0,1] neg_hi:[0,1]
	v_pk_add_f32 v[90:91], v[90:91], v[36:37] op_sel_hi:[1,0] neg_lo:[0,1] neg_hi:[0,1]
	v_pk_add_f32 v[74:75], v[74:75], v[36:37] op_sel_hi:[1,0] neg_lo:[0,1] neg_hi:[0,1]
	v_pk_add_f32 v[92:93], v[92:93], v[36:37] op_sel_hi:[1,0] neg_lo:[0,1] neg_hi:[0,1]
	v_pk_add_f32 v[76:77], v[76:77], v[36:37] op_sel_hi:[1,0] neg_lo:[0,1] neg_hi:[0,1]
	v_pk_add_f32 v[94:95], v[94:95], v[36:37] op_sel_hi:[1,0] neg_lo:[0,1] neg_hi:[0,1]
	v_pk_add_f32 v[78:79], v[78:79], v[36:37] op_sel_hi:[1,0] neg_lo:[0,1] neg_hi:[0,1]
	v_pk_add_f32 v[96:97], v[96:97], v[36:37] op_sel_hi:[1,0] neg_lo:[0,1] neg_hi:[0,1]
	v_pk_add_f32 v[80:81], v[80:81], v[36:37] op_sel_hi:[1,0] neg_lo:[0,1] neg_hi:[0,1]
	v_pk_mul_f32 v[32:33], v[32:33], v[38:39] op_sel_hi:[1,0]
	v_pk_mul_f32 v[30:31], v[30:31], v[38:39] op_sel_hi:[1,0]
	v_pk_mul_f32 v[28:29], v[28:29], v[38:39] op_sel_hi:[1,0]
	v_pk_mul_f32 v[26:27], v[26:27], v[38:39] op_sel_hi:[1,0]
	v_pk_mul_f32 v[24:25], v[24:25], v[38:39] op_sel_hi:[1,0]
	v_pk_mul_f32 v[22:23], v[22:23], v[38:39] op_sel_hi:[1,0]
	v_pk_mul_f32 v[20:21], v[20:21], v[38:39] op_sel_hi:[1,0]
	v_pk_mul_f32 v[18:19], v[18:19], v[38:39] op_sel_hi:[1,0]
	v_pk_mul_f32 v[16:17], v[16:17], v[38:39] op_sel_hi:[1,0]
	v_pk_mul_f32 v[14:15], v[14:15], v[38:39] op_sel_hi:[1,0]
	v_pk_mul_f32 v[12:13], v[12:13], v[38:39] op_sel_hi:[1,0]
	v_pk_mul_f32 v[10:11], v[10:11], v[38:39] op_sel_hi:[1,0]
	v_pk_mul_f32 v[8:9], v[8:9], v[38:39] op_sel_hi:[1,0]
	v_pk_mul_f32 v[6:7], v[6:7], v[38:39] op_sel_hi:[1,0]
	v_pk_mul_f32 v[4:5], v[4:5], v[38:39] op_sel_hi:[1,0]
	v_pk_mul_f32 v[2:3], v[2:3], v[38:39] op_sel_hi:[1,0]
	v_mul_f32_e32 v164, v164, v38
	v_mov_b32_e32 v35, v34
	v_mov_b32_e32 v36, v34
	v_mov_b32_e32 v37, v34
	v_mov_b32_e32 v38, v34
	v_mov_b32_e32 v39, v34
	v_mov_b32_e32 v40, v34
	v_mov_b32_e32 v41, v34
	v_mov_b32_e32 v42, v34
	v_mov_b32_e32 v43, v34
	v_mov_b32_e32 v44, v34
	v_mov_b32_e32 v45, v34
	v_mov_b32_e32 v46, v34
	v_mov_b32_e32 v47, v34
	v_mov_b32_e32 v48, v34
	v_mov_b32_e32 v49, v34
	v_mov_b32_e32 v50, v34
	v_mov_b32_e32 v51, v34
	v_mov_b32_e32 v52, v34
	v_mov_b32_e32 v53, v34
	v_mov_b32_e32 v54, v34
	v_mov_b32_e32 v55, v34
	v_mov_b32_e32 v56, v34
	v_mov_b32_e32 v57, v34
	v_mov_b32_e32 v58, v34
	v_mov_b32_e32 v59, v34
	v_mov_b32_e32 v60, v34
	v_mov_b32_e32 v61, v34
	v_mov_b32_e32 v62, v34
	v_mov_b32_e32 v63, v34
	v_mov_b32_e32 v64, v34
	v_mov_b32_e32 v65, v34
	s_branch .LBB0_645
; template <int DQK, int DV, bool BIAS> ...
;     ...
;         const LAS unsigned char* kb = lds + buf * KBUF + r32 * KP + hi * 16;
; #pragma unroll
;         for (int ks = 0; ks < NKS; ++ks) {
;             const bf16x8 k0 = *(const LAS bf16x8*)(kb + ks * 32), k1 = *(const LAS bf16x8*)(kb + 32 * KP + ks * 32);
;             if (ks == 0) { p0 = __builtin_amdgcn_mfma_f32_32x32x16_bf16(k0, qf[0], negm, 0, 0, 0); p1 = __builtin_amdgcn_mfma_f32_32x32x16_bf16(k1, qf[0], negm, 0, 0, 0); }
;             else { p0 = __builtin_amdgcn_mfma_f32_32x32x16_bf16(k0, qf[ks], p0, 0, 0, 0); p1 = __builtin_amdgcn_mfma_f32_32x32x16_bf16(k1, qf[ks], p1, 0, 0, 0); }
;         }
;         if (BIAS) {
;             asm volatile("s_nop 15\n\ts_nop 7" : "+v"(p0), "+v"(p1));
;             const float d0 = qp - (float)(t * 64 + 4 * hi);
; #pragma unroll
;             for (int r = 0; r < 16; ++r) { const float dk = d0 - (float)((r & 3) + 8 * (r >> 2)); p0[r] = p0[r] - sl2 * fabsf(dk); p1[r] = p1[r] - sl2 * fabsf(dk - 32.f); }
;         } else {
;             asm volatile("s_nop 15\n\ts_nop 7" : "+v"(p0), "+v"(p1));
;         }
;     ...
;         if (!isY) {
;             const LAS unsigned char* vbase = lds + VOFF + vcur * VBUF + (4 * hi + ((lane & 15) >> 2)) * 64 + ((lane >> 4) & 1) * 32 + (lane & 3) * 8;
;             float ls = 0.f;
; #pragma unroll
;             for (int hs = 0; hs < 4; ++hs) {
;                 float e[8];
; #pragma unroll
;                 for (int j = 0; j < 8; ++j) { e[j] = __builtin_amdgcn_exp2f(hs < 2 ? p0[8 * (hs & 1) + j] : p1[8 * (hs & 1) + j]); ls += e[j]; }
;                 pw[hs].x = cvtpk(e[0], e[1]); pw[hs].y = cvtpk(e[2], e[3]); pw[hs].z = cvtpk(e[4], e[5]); pw[hs].w = cvtpk(e[6], e[7]);
;                 const bf16x8 pbv = __builtin_bit_cast(bf16x8, pw[hs]);
; #pragma unroll
;                 for (int d = 0; d < NDT; ++d) { const LAS unsigned char* vp = vbase + d * 4096 + hs * 1024;
;                     const v4i16_t a0 = __builtin_amdgcn_ds_read_tr16_b64_v4i16((LAS v4i16_t*)vp), a1 = __builtin_amdgcn_ds_read_tr16_b64_v4i16((LAS v4i16_t*)(vp + 512));
;                     const bf16x8 av = {a0[0], a0[1], a0[2], a0[3], a1[0], a1[1], a1[2], a1[3]};
;                     o[d] = __builtin_amdgcn_mfma_f32_32x32x16_bf16(av, pbv, o[d], 0, 0, 0); }
;                 __builtin_amdgcn_sched_barrier(0);
;             }
;             l += ls;
.LBB0_644:
.LBB0_645:
	v_exp_f32_e32 v165, v82
	v_exp_f32_e32 v166, v83
	v_exp_f32_e32 v167, v84
	v_exp_f32_e32 v169, v85
	v_exp_f32_e32 v174, v86
	v_exp_f32_e32 v175, v87
	ds_read_b64_tr_b16 v[82:83], v161 offset:53248
	ds_read_b64_tr_b16 v[84:85], v161 offset:53760
	v_exp_f32_e32 v176, v88
	v_exp_f32_e32 v177, v89
	ds_read_b64_tr_b16 v[170:171], v161 offset:57344
	ds_read_b64_tr_b16 v[172:173], v161 offset:57856
	v_cvt_pk_bf16_f32 v86, v165, v166
	v_cvt_pk_bf16_f32 v87, v167, v169
	v_cvt_pk_bf16_f32 v88, v174, v175
	v_cvt_pk_bf16_f32 v89, v176, v177
	s_waitcnt lgkmcnt(2)
	s_nop 0
	v_mfma_f32_32x32x16_bf16 v[18:33], v[82:85], v[86:89], v[18:33]
	v_add_f32_e32 v82, v166, v165
	v_add_f32_e32 v82, v167, v82
	v_add_f32_e32 v82, v169, v82
	v_add_f32_e32 v82, v174, v82
	v_add_f32_e32 v82, v175, v82
	v_add_f32_e32 v82, v176, v82
	s_waitcnt lgkmcnt(0)
	v_mfma_f32_32x32x16_bf16 v[2:17], v[170:173], v[86:89], v[2:17]
	v_add_f32_e32 v165, v177, v82
	v_exp_f32_e32 v166, v90
	v_exp_f32_e32 v167, v91
	v_exp_f32_e32 v169, v92
	v_exp_f32_e32 v170, v93
	v_exp_f32_e32 v94, v94
	v_exp_f32_e32 v95, v95
	ds_read_b64_tr_b16 v[82:83], v161 offset:54272
	ds_read_b64_tr_b16 v[84:85], v161 offset:54784
	v_exp_f32_e32 v96, v96
	v_exp_f32_e32 v97, v97
	ds_read_b64_tr_b16 v[90:91], v161 offset:58368
	ds_read_b64_tr_b16 v[92:93], v161 offset:58880
	v_cvt_pk_bf16_f32 v86, v166, v167
	v_cvt_pk_bf16_f32 v87, v169, v170
	v_cvt_pk_bf16_f32 v88, v94, v95
	v_cvt_pk_bf16_f32 v89, v96, v97
	s_waitcnt lgkmcnt(2)
	s_nop 0
	v_mfma_f32_32x32x16_bf16 v[18:33], v[82:85], v[86:89], v[18:33]
	v_add_f32_e32 v82, v166, v165
	v_add_f32_e32 v82, v167, v82
	v_add_f32_e32 v82, v169, v82
	v_add_f32_e32 v82, v170, v82
	v_add_f32_e32 v82, v94, v82
	v_add_f32_e32 v82, v95, v82
	v_add_f32_e32 v82, v96, v82
	s_waitcnt lgkmcnt(0)
	v_mfma_f32_32x32x16_bf16 v[2:17], v[90:93], v[86:89], v[2:17]
	v_add_f32_e32 v86, v97, v82
	v_exp_f32_e32 v87, v66
	v_exp_f32_e32 v88, v67
	v_exp_f32_e32 v89, v68
	v_exp_f32_e32 v90, v69
	v_exp_f32_e32 v91, v70
	v_exp_f32_e32 v92, v71
	ds_read_b64_tr_b16 v[66:67], v161 offset:55296
	ds_read_b64_tr_b16 v[68:69], v161 offset:55808
	v_exp_f32_e32 v93, v72
	v_exp_f32_e32 v94, v73
	ds_read_b64_tr_b16 v[82:83], v161 offset:59392
	ds_read_b64_tr_b16 v[84:85], v161 offset:59904
	v_cvt_pk_bf16_f32 v70, v87, v88
	v_cvt_pk_bf16_f32 v71, v89, v90
	v_cvt_pk_bf16_f32 v72, v91, v92
	v_cvt_pk_bf16_f32 v73, v93, v94
	s_waitcnt lgkmcnt(2)
	s_nop 0
	v_mfma_f32_32x32x16_bf16 v[18:33], v[66:69], v[70:73], v[18:33]
	v_add_f32_e32 v66, v87, v86
	v_add_f32_e32 v66, v88, v66
	v_add_f32_e32 v66, v89, v66
	v_add_f32_e32 v66, v90, v66
	v_add_f32_e32 v66, v91, v66
	v_add_f32_e32 v66, v92, v66
	v_add_f32_e32 v66, v93, v66
	s_waitcnt lgkmcnt(0)
	v_mfma_f32_32x32x16_bf16 v[2:17], v[82:85], v[70:73], v[2:17]
	v_add_f32_e32 v82, v94, v66
	v_exp_f32_e32 v83, v74
	v_exp_f32_e32 v84, v75
	v_exp_f32_e32 v85, v76
	v_exp_f32_e32 v86, v77
	v_exp_f32_e32 v78, v78
	v_exp_f32_e32 v79, v79
	ds_read_b64_tr_b16 v[66:67], v161 offset:56320
	ds_read_b64_tr_b16 v[68:69], v161 offset:56832
	v_exp_f32_e32 v80, v80
	v_exp_f32_e32 v81, v81
	ds_read_b64_tr_b16 v[74:75], v161 offset:60416
	ds_read_b64_tr_b16 v[76:77], v161 offset:60928
	v_cvt_pk_bf16_f32 v70, v83, v84
	v_cvt_pk_bf16_f32 v71, v85, v86
	v_cvt_pk_bf16_f32 v72, v78, v79
	v_cvt_pk_bf16_f32 v73, v80, v81
	s_waitcnt lgkmcnt(2)
	s_nop 0
	v_mfma_f32_32x32x16_bf16 v[18:33], v[66:69], v[70:73], v[18:33]
	v_add_f32_e32 v66, v83, v82
	v_add_f32_e32 v66, v84, v66
	v_add_f32_e32 v66, v85, v66
	v_add_f32_e32 v66, v86, v66
	v_add_f32_e32 v66, v78, v66
	v_add_f32_e32 v66, v79, v66
	v_add_f32_e32 v66, v80, v66
	s_waitcnt lgkmcnt(0)
	v_mfma_f32_32x32x16_bf16 v[2:17], v[74:77], v[70:73], v[2:17]
	v_add_f32_e32 v165, v81, v66
	ds_read_b128 v[66:69], v148 offset:13312
	ds_read_b128 v[170:173], v148 offset:13344
	ds_read_b128 v[174:177], v148 offset:19968
	ds_read_b128 v[178:181], v148 offset:20000
	v_add_f32_e32 v164, v164, v165
	s_waitcnt lgkmcnt(3)
	v_mfma_f32_32x32x16_bf16 v[82:97], v[66:69], v[98:101], v[34:49]
	s_waitcnt lgkmcnt(1)
	v_mfma_f32_32x32x16_bf16 v[66:81], v[174:177], v[98:101], v[34:49]
	v_mfma_f32_32x32x16_bf16 v[82:97], v[170:173], v[102:105], v[82:97]
	ds_read_b128 v[170:173], v148 offset:13376
	ds_read_b128 v[174:177], v148 offset:13408
	s_waitcnt lgkmcnt(2)
	v_mfma_f32_32x32x16_bf16 v[66:81], v[178:181], v[102:105], v[66:81]
	s_waitcnt lgkmcnt(1)
	v_mfma_f32_32x32x16_bf16 v[82:97], v[170:173], v[106:109], v[82:97]
	ds_read_b128 v[170:173], v148 offset:20032
	ds_read_b128 v[178:181], v148 offset:20064
	s_waitcnt lgkmcnt(1)
	v_mfma_f32_32x32x16_bf16 v[66:81], v[170:173], v[106:109], v[66:81]
	v_mfma_f32_32x32x16_bf16 v[82:97], v[174:177], v[110:113], v[82:97]
	ds_read_b128 v[170:173], v148 offset:13440
	ds_read_b128 v[174:177], v148 offset:13472
	s_waitcnt lgkmcnt(2)
	v_mfma_f32_32x32x16_bf16 v[66:81], v[178:181], v[110:113], v[66:81]
	s_waitcnt lgkmcnt(1)
	v_mfma_f32_32x32x16_bf16 v[82:97], v[170:173], v[114:117], v[82:97]
	ds_read_b128 v[170:173], v148 offset:20096
	ds_read_b128 v[178:181], v148 offset:20128
	s_waitcnt lgkmcnt(1)
	v_mfma_f32_32x32x16_bf16 v[66:81], v[170:173], v[114:117], v[66:81]
	v_mfma_f32_32x32x16_bf16 v[82:97], v[174:177], v[118:121], v[82:97]
	s_waitcnt lgkmcnt(0)
	v_mfma_f32_32x32x16_bf16 v[66:81], v[178:181], v[118:121], v[66:81]
	s_nop 15
	s_nop 7
	s_nop 0
	v_max3_f32 v165, v82, v83, v66
	v_max3_f32 v166, v84, v85, v67
	v_max3_f32 v165, v165, v68, v69
	v_max3_f32 v166, v166, v88, v89
	v_max3_f32 v165, v165, v86, v87
	v_max3_f32 v166, v166, v72, v73
	v_max3_f32 v165, v165, v70, v71
	v_max3_f32 v166, v166, v92, v93
	v_max3_f32 v165, v165, v90, v91
	v_max3_f32 v166, v166, v76, v77
	v_max3_f32 v165, v165, v74, v75
	v_max3_f32 v166, v166, v96, v97
	v_max3_f32 v165, v165, v94, v95
	v_max3_f32 v166, v166, v80, v81
	v_max3_f32 v165, v165, v78, v79
	v_max_f32_e32 v165, v165, v166
	v_cmp_lt_f32_e32 vcc, s59, v165
	s_cbranch_vccz .LBB0_647
; template <int DQK, int DV, bool BIAS> ...
;     ...
;         if (__any(mx > 8.f)) {
;             mx = fmaxf(mx, __shfl_xor(mx, 32));
;             const float dl = fmaxf(mx, 0.f); mhat += dl;
;             const float f = __builtin_amdgcn_exp2f(-dl);
; #pragma unroll
;             for (int r = 0; r < 16; ++r) { p0[r] -= dl; p1[r] -= dl; negm[r] = -mhat; }
;             l *= f;
; #pragma unroll
;             for (int d = 0; d < NDT; ++d)
; #pragma unroll
;                 for (int r = 0; r < 16; ++r) o[d][r] *= f;
;         }
	ds_bpermute_b32 v34, v168, v165
	s_waitcnt lgkmcnt(0)
	v_max3_f32 v36, v165, v34, 0
	v_exp_f32_e64 v38, -v36
	v_add_f32_e32 v153, v153, v36
	v_xor_b32_e32 v34, 0x80000000, v153
	v_pk_add_f32 v[82:83], v[82:83], v[36:37] op_sel_hi:[1,0] neg_lo:[0,1] neg_hi:[0,1]
	v_pk_add_f32 v[66:67], v[66:67], v[36:37] op_sel_hi:[1,0] neg_lo:[0,1] neg_hi:[0,1]
	v_pk_add_f32 v[84:85], v[84:85], v[36:37] op_sel_hi:[1,0] neg_lo:[0,1] neg_hi:[0,1]
	v_pk_add_f32 v[68:69], v[68:69], v[36:37] op_sel_hi:[1,0] neg_lo:[0,1] neg_hi:[0,1]
	v_pk_add_f32 v[86:87], v[86:87], v[36:37] op_sel_hi:[1,0] neg_lo:[0,1] neg_hi:[0,1]
	v_pk_add_f32 v[70:71], v[70:71], v[36:37] op_sel_hi:[1,0] neg_lo:[0,1] neg_hi:[0,1]
	v_pk_add_f32 v[88:89], v[88:89], v[36:37] op_sel_hi:[1,0] neg_lo:[0,1] neg_hi:[0,1]
	v_pk_add_f32 v[72:73], v[72:73], v[36:37] op_sel_hi:[1,0] neg_lo:[0,1] neg_hi:[0,1]
	v_pk_add_f32 v[90:91], v[90:91], v[36:37] op_sel_hi:[1,0] neg_lo:[0,1] neg_hi:[0,1]
	v_pk_add_f32 v[74:75], v[74:75], v[36:37] op_sel_hi:[1,0] neg_lo:[0,1] neg_hi:[0,1]
	v_pk_add_f32 v[92:93], v[92:93], v[36:37] op_sel_hi:[1,0] neg_lo:[0,1] neg_hi:[0,1]
	v_pk_add_f32 v[76:77], v[76:77], v[36:37] op_sel_hi:[1,0] neg_lo:[0,1] neg_hi:[0,1]
	v_pk_add_f32 v[94:95], v[94:95], v[36:37] op_sel_hi:[1,0] neg_lo:[0,1] neg_hi:[0,1]
	v_pk_add_f32 v[78:79], v[78:79], v[36:37] op_sel_hi:[1,0] neg_lo:[0,1] neg_hi:[0,1]
	v_pk_add_f32 v[96:97], v[96:97], v[36:37] op_sel_hi:[1,0] neg_lo:[0,1] neg_hi:[0,1]
	v_pk_add_f32 v[80:81], v[80:81], v[36:37] op_sel_hi:[1,0] neg_lo:[0,1] neg_hi:[0,1]
	v_pk_mul_f32 v[32:33], v[32:33], v[38:39] op_sel_hi:[1,0]
	v_pk_mul_f32 v[30:31], v[30:31], v[38:39] op_sel_hi:[1,0]
	v_pk_mul_f32 v[28:29], v[28:29], v[38:39] op_sel_hi:[1,0]
	v_pk_mul_f32 v[26:27], v[26:27], v[38:39] op_sel_hi:[1,0]
	v_pk_mul_f32 v[24:25], v[24:25], v[38:39] op_sel_hi:[1,0]
	v_pk_mul_f32 v[22:23], v[22:23], v[38:39] op_sel_hi:[1,0]
	v_pk_mul_f32 v[20:21], v[20:21], v[38:39] op_sel_hi:[1,0]
	v_pk_mul_f32 v[18:19], v[18:19], v[38:39] op_sel_hi:[1,0]
	v_pk_mul_f32 v[16:17], v[16:17], v[38:39] op_sel_hi:[1,0]
	v_pk_mul_f32 v[14:15], v[14:15], v[38:39] op_sel_hi:[1,0]
	v_pk_mul_f32 v[12:13], v[12:13], v[38:39] op_sel_hi:[1,0]
	v_pk_mul_f32 v[10:11], v[10:11], v[38:39] op_sel_hi:[1,0]
	v_pk_mul_f32 v[8:9], v[8:9], v[38:39] op_sel_hi:[1,0]
	v_pk_mul_f32 v[6:7], v[6:7], v[38:39] op_sel_hi:[1,0]
	v_pk_mul_f32 v[4:5], v[4:5], v[38:39] op_sel_hi:[1,0]
	v_pk_mul_f32 v[2:3], v[2:3], v[38:39] op_sel_hi:[1,0]
	v_mul_f32_e32 v164, v164, v38
	v_mov_b32_e32 v35, v34
	v_mov_b32_e32 v36, v34
	v_mov_b32_e32 v37, v34
	v_mov_b32_e32 v38, v34
	v_mov_b32_e32 v39, v34
	v_mov_b32_e32 v40, v34
	v_mov_b32_e32 v41, v34
	v_mov_b32_e32 v42, v34
	v_mov_b32_e32 v43, v34
	v_mov_b32_e32 v44, v34
	v_mov_b32_e32 v45, v34
	v_mov_b32_e32 v46, v34
	v_mov_b32_e32 v47, v34
	v_mov_b32_e32 v48, v34
	v_mov_b32_e32 v49, v34
	v_mov_b32_e32 v50, v34
	v_mov_b32_e32 v51, v34
	v_mov_b32_e32 v52, v34
	v_mov_b32_e32 v53, v34
	v_mov_b32_e32 v54, v34
	v_mov_b32_e32 v55, v34
	v_mov_b32_e32 v56, v34
	v_mov_b32_e32 v57, v34
	v_mov_b32_e32 v58, v34
	v_mov_b32_e32 v59, v34
	v_mov_b32_e32 v60, v34
	v_mov_b32_e32 v61, v34
	v_mov_b32_e32 v62, v34
	v_mov_b32_e32 v63, v34
	v_mov_b32_e32 v64, v34
	v_mov_b32_e32 v65, v34

; template <int DQK, int DV, bool BIAS> ...
;     ...
;         const LAS unsigned char* kb = lds + buf * KBUF + r32 * KP + hi * 16;
; #pragma unroll
;         for (int ks = 0; ks < NKS; ++ks) {
;             const bf16x8 k0 = *(const LAS bf16x8*)(kb + ks * 32), k1 = *(const LAS bf16x8*)(kb + 32 * KP + ks * 32);
;             if (ks == 0) { p0 = __builtin_amdgcn_mfma_f32_32x32x16_bf16(k0, qf[0], negm, 0, 0, 0); p1 = __builtin_amdgcn_mfma_f32_32x32x16_bf16(k1, qf[0], negm, 0, 0, 0); }
;             else { p0 = __builtin_amdgcn_mfma_f32_32x32x16_bf16(k0, qf[ks], p0, 0, 0, 0); p1 = __builtin_amdgcn_mfma_f32_32x32x16_bf16(k1, qf[ks], p1, 0, 0, 0); }
;         }
;         if (BIAS) {
;             asm volatile("s_nop 15\n\ts_nop 7" : "+v"(p0), "+v"(p1));
;             const float d0 = qp - (float)(t * 64 + 4 * hi);
; #pragma unroll
;             for (int r = 0; r < 16; ++r) { const float dk = d0 - (float)((r & 3) + 8 * (r >> 2)); p0[r] = p0[r] - sl2 * fabsf(dk); p1[r] = p1[r] - sl2 * fabsf(dk - 32.f); }
;         } else {
;             asm volatile("s_nop 15\n\ts_nop 7" : "+v"(p0), "+v"(p1));
;         }
;     ...
;         if (!isY) {
;             const LAS unsigned char* vbase = lds + VOFF + vcur * VBUF + (4 * hi + ((lane & 15) >> 2)) * 64 + ((lane >> 4) & 1) * 32 + (lane & 3) * 8;
;             float ls = 0.f;
; #pragma unroll
;             for (int hs = 0; hs < 4; ++hs) {
;                 float e[8];
; #pragma unroll
;                 for (int j = 0; j < 8; ++j) { e[j] = __builtin_amdgcn_exp2f(hs < 2 ? p0[8 * (hs & 1) + j] : p1[8 * (hs & 1) + j]); ls += e[j]; }
;                 pw[hs].x = cvtpk(e[0], e[1]); pw[hs].y = cvtpk(e[2], e[3]); pw[hs].z = cvtpk(e[4], e[5]); pw[hs].w = cvtpk(e[6], e[7]);
;                 const bf16x8 pbv = __builtin_bit_cast(bf16x8, pw[hs]);
; #pragma unroll
;                 for (int d = 0; d < NDT; ++d) { const LAS unsigned char* vp = vbase + d * 4096 + hs * 1024;
;                     const v4i16_t a0 = __builtin_amdgcn_ds_read_tr16_b64_v4i16((LAS v4i16_t*)vp), a1 = __builtin_amdgcn_ds_read_tr16_b64_v4i16((LAS v4i16_t*)(vp + 512));
;                     const bf16x8 av = {a0[0], a0[1], a0[2], a0[3], a1[0], a1[1], a1[2], a1[3]};
;                     o[d] = __builtin_amdgcn_mfma_f32_32x32x16_bf16(av, pbv, o[d], 0, 0, 0); }
;                 __builtin_amdgcn_sched_barrier(0);
;             }
;             l += ls;
.LBB0_660:
	v_exp_f32_e32 v165, v82
	v_exp_f32_e32 v166, v83
	v_exp_f32_e32 v167, v84
	v_exp_f32_e32 v169, v85
	v_exp_f32_e32 v174, v86
	v_exp_f32_e32 v175, v87
	ds_read_b64_tr_b16 v[82:83], v162 offset:16384
	ds_read_b64_tr_b16 v[84:85], v162 offset:16896
	v_exp_f32_e32 v176, v88
	v_exp_f32_e32 v177, v89
	ds_read_b64_tr_b16 v[170:171], v162 offset:20480
	ds_read_b64_tr_b16 v[172:173], v162 offset:20992
	v_cvt_pk_bf16_f32 v86, v165, v166
	v_cvt_pk_bf16_f32 v87, v167, v169
	v_cvt_pk_bf16_f32 v88, v174, v175
	v_cvt_pk_bf16_f32 v89, v176, v177
	s_waitcnt lgkmcnt(2)
	s_nop 0
	v_mfma_f32_32x32x16_bf16 v[18:33], v[82:85], v[86:89], v[18:33]
	v_add_f32_e32 v82, v166, v165
	v_add_f32_e32 v82, v167, v82
	v_add_f32_e32 v82, v169, v82
	v_add_f32_e32 v82, v174, v82
	v_add_f32_e32 v82, v175, v82
	v_add_f32_e32 v82, v176, v82
	s_waitcnt lgkmcnt(0)
	v_mfma_f32_32x32x16_bf16 v[2:17], v[170:173], v[86:89], v[2:17]
	v_add_f32_e32 v165, v177, v82
	v_exp_f32_e32 v166, v90
	v_exp_f32_e32 v167, v91
	v_exp_f32_e32 v169, v92
	v_exp_f32_e32 v170, v93
	v_exp_f32_e32 v94, v94
	v_exp_f32_e32 v95, v95
	ds_read_b64_tr_b16 v[82:83], v162 offset:17408
	ds_read_b64_tr_b16 v[84:85], v162 offset:17920
	v_exp_f32_e32 v96, v96
	v_exp_f32_e32 v97, v97
	ds_read_b64_tr_b16 v[90:91], v162 offset:21504
	ds_read_b64_tr_b16 v[92:93], v162 offset:22016
	v_cvt_pk_bf16_f32 v86, v166, v167
	v_cvt_pk_bf16_f32 v87, v169, v170
	v_cvt_pk_bf16_f32 v88, v94, v95
	v_cvt_pk_bf16_f32 v89, v96, v97
	s_waitcnt lgkmcnt(2)
	s_nop 0
	v_mfma_f32_32x32x16_bf16 v[18:33], v[82:85], v[86:89], v[18:33]
	v_add_f32_e32 v82, v166, v165
	v_add_f32_e32 v82, v167, v82
	v_add_f32_e32 v82, v169, v82
	v_add_f32_e32 v82, v170, v82
	v_add_f32_e32 v82, v94, v82
	v_add_f32_e32 v82, v95, v82
	v_add_f32_e32 v82, v96, v82
	s_waitcnt lgkmcnt(0)
	v_mfma_f32_32x32x16_bf16 v[2:17], v[90:93], v[86:89], v[2:17]
	v_add_f32_e32 v86, v97, v82
	v_exp_f32_e32 v87, v66
	v_exp_f32_e32 v88, v67
	v_exp_f32_e32 v89, v68
	v_exp_f32_e32 v90, v69
	v_exp_f32_e32 v91, v70
	v_exp_f32_e32 v92, v71
	ds_read_b64_tr_b16 v[66:67], v162 offset:18432
	ds_read_b64_tr_b16 v[68:69], v162 offset:18944
	v_exp_f32_e32 v93, v72
	v_exp_f32_e32 v94, v73
	ds_read_b64_tr_b16 v[82:83], v162 offset:22528
	ds_read_b64_tr_b16 v[84:85], v162 offset:23040
	v_cvt_pk_bf16_f32 v70, v87, v88
	v_cvt_pk_bf16_f32 v71, v89, v90
	v_cvt_pk_bf16_f32 v72, v91, v92
	v_cvt_pk_bf16_f32 v73, v93, v94
	s_waitcnt lgkmcnt(2)
	s_nop 0
	v_mfma_f32_32x32x16_bf16 v[18:33], v[66:69], v[70:73], v[18:33]
	v_add_f32_e32 v66, v87, v86
	v_add_f32_e32 v66, v88, v66
	v_add_f32_e32 v66, v89, v66
	v_add_f32_e32 v66, v90, v66
	v_add_f32_e32 v66, v91, v66
	v_add_f32_e32 v66, v92, v66
	v_add_f32_e32 v66, v93, v66
	s_waitcnt lgkmcnt(0)
	v_mfma_f32_32x32x16_bf16 v[2:17], v[82:85], v[70:73], v[2:17]
	v_add_f32_e32 v82, v94, v66
	v_exp_f32_e32 v83, v74
	v_exp_f32_e32 v84, v75
	v_exp_f32_e32 v85, v76
	v_exp_f32_e32 v86, v77
	v_exp_f32_e32 v78, v78
	v_exp_f32_e32 v79, v79
	ds_read_b64_tr_b16 v[66:67], v162 offset:19456
	ds_read_b64_tr_b16 v[68:69], v162 offset:19968
	v_exp_f32_e32 v80, v80
	v_exp_f32_e32 v81, v81
	ds_read_b64_tr_b16 v[74:75], v162 offset:23552
	ds_read_b64_tr_b16 v[76:77], v162 offset:24064
	v_cvt_pk_bf16_f32 v70, v83, v84
	v_cvt_pk_bf16_f32 v71, v85, v86
	v_cvt_pk_bf16_f32 v72, v78, v79
	v_cvt_pk_bf16_f32 v73, v80, v81
	s_waitcnt lgkmcnt(2)
	s_nop 0
	v_mfma_f32_32x32x16_bf16 v[18:33], v[66:69], v[70:73], v[18:33]
	v_add_f32_e32 v66, v83, v82
	v_add_f32_e32 v66, v84, v66
	v_add_f32_e32 v66, v85, v66
	v_add_f32_e32 v66, v86, v66
	v_add_f32_e32 v66, v78, v66
	v_add_f32_e32 v66, v79, v66
	v_add_f32_e32 v66, v80, v66
	s_waitcnt lgkmcnt(0)
	v_mfma_f32_32x32x16_bf16 v[2:17], v[74:77], v[70:73], v[2:17]
	v_add_f32_e32 v94, v81, v66
	ds_read_b128 v[82:85], v148 offset:39936
	ds_read_b128 v[86:89], v148 offset:39968
	s_waitcnt lgkmcnt(1)
	v_mfma_f32_32x32x16_bf16 v[66:81], v[82:85], v[98:101], v[34:49]
	ds_read_b128 v[82:85], v148 offset:46592
	ds_read_b128 v[90:93], v148 offset:46624
	s_waitcnt lgkmcnt(1)
	v_mfma_f32_32x32x16_bf16 v[208:223], v[82:85], v[98:101], v[34:49]
	v_mfma_f32_32x32x16_bf16 v[66:81], v[86:89], v[102:105], v[66:81]
	ds_read_b128 v[82:85], v148 offset:40000
	ds_read_b128 v[86:89], v148 offset:40032
	s_waitcnt lgkmcnt(2)
	v_mfma_f32_32x32x16_bf16 v[208:223], v[90:93], v[102:105], v[208:223]
	s_waitcnt lgkmcnt(1)
	v_mfma_f32_32x32x16_bf16 v[66:81], v[82:85], v[106:109], v[66:81]
	ds_read_b128 v[82:85], v148 offset:46656
	ds_read_b128 v[90:93], v148 offset:46688
	s_waitcnt lgkmcnt(1)
	v_mfma_f32_32x32x16_bf16 v[208:223], v[82:85], v[106:109], v[208:223]
	v_mfma_f32_32x32x16_bf16 v[66:81], v[86:89], v[110:113], v[66:81]
	ds_read_b128 v[82:85], v148 offset:40064
	ds_read_b128 v[86:89], v148 offset:40096
	s_waitcnt lgkmcnt(2)
	v_mfma_f32_32x32x16_bf16 v[208:223], v[90:93], v[110:113], v[208:223]
	s_waitcnt lgkmcnt(1)
	v_mfma_f32_32x32x16_bf16 v[66:81], v[82:85], v[114:117], v[66:81]
	ds_read_b128 v[82:85], v148 offset:46720
	ds_read_b128 v[90:93], v148 offset:46752
	s_waitcnt lgkmcnt(1)
	v_mfma_f32_32x32x16_bf16 v[208:223], v[82:85], v[114:117], v[208:223]
	v_add_f32_e32 v82, v164, v94
	v_mfma_f32_32x32x16_bf16 v[66:81], v[86:89], v[118:121], v[66:81]
	s_waitcnt lgkmcnt(0)
	v_mfma_f32_32x32x16_bf16 v[208:223], v[90:93], v[118:121], v[208:223]
	s_nop 15
	s_nop 7
	s_nop 0
	v_max3_f32 v83, v66, v67, v208
	v_max3_f32 v84, v68, v69, v209
	v_max3_f32 v83, v83, v210, v211
	v_max3_f32 v84, v84, v72, v73
	v_max3_f32 v83, v83, v70, v71
	v_max3_f32 v84, v84, v214, v215
	v_max3_f32 v83, v83, v212, v213
	v_max3_f32 v84, v84, v76, v77
	v_max3_f32 v83, v83, v74, v75
	v_max3_f32 v84, v84, v218, v219
	v_max3_f32 v83, v83, v216, v217
	v_max3_f32 v84, v84, v80, v81
	v_max3_f32 v83, v83, v78, v79
	v_max3_f32 v84, v84, v222, v223
	v_max3_f32 v83, v83, v220, v221
	v_max_f32_e32 v83, v83, v84
	v_cmp_lt_f32_e32 vcc, s59, v83
	s_cbranch_vccz .LBB0_631
; template <int DQK, int DV, bool BIAS> ...
;     ...
;         if (__any(mx > 8.f)) {
;             mx = fmaxf(mx, __shfl_xor(mx, 32));
;             const float dl = fmaxf(mx, 0.f); mhat += dl;
;             const float f = __builtin_amdgcn_exp2f(-dl);
; #pragma unroll
;             for (int r = 0; r < 16; ++r) { p0[r] -= dl; p1[r] -= dl; negm[r] = -mhat; }
;             l *= f;
; #pragma unroll
;             for (int d = 0; d < NDT; ++d)
; #pragma unroll
;                 for (int r = 0; r < 16; ++r) o[d][r] *= f;
;         }
	ds_bpermute_b32 v50, v168, v83
	s_waitcnt lgkmcnt(0)
	v_max3_f32 v52, v83, v50, 0
	v_exp_f32_e64 v54, -v52
	v_add_f32_e32 v153, v153, v52
	v_xor_b32_e32 v50, 0x80000000, v153
	v_pk_add_f32 v[66:67], v[66:67], v[52:53] op_sel_hi:[1,0] neg_lo:[0,1] neg_hi:[0,1]
	v_pk_add_f32 v[208:209], v[208:209], v[52:53] op_sel_hi:[1,0] neg_lo:[0,1] neg_hi:[0,1]
	v_pk_add_f32 v[68:69], v[68:69], v[52:53] op_sel_hi:[1,0] neg_lo:[0,1] neg_hi:[0,1]
	v_pk_add_f32 v[210:211], v[210:211], v[52:53] op_sel_hi:[1,0] neg_lo:[0,1] neg_hi:[0,1]
	v_pk_add_f32 v[70:71], v[70:71], v[52:53] op_sel_hi:[1,0] neg_lo:[0,1] neg_hi:[0,1]
	v_pk_add_f32 v[212:213], v[212:213], v[52:53] op_sel_hi:[1,0] neg_lo:[0,1] neg_hi:[0,1]
	v_pk_add_f32 v[72:73], v[72:73], v[52:53] op_sel_hi:[1,0] neg_lo:[0,1] neg_hi:[0,1]
	v_pk_add_f32 v[214:215], v[214:215], v[52:53] op_sel_hi:[1,0] neg_lo:[0,1] neg_hi:[0,1]
	v_pk_add_f32 v[74:75], v[74:75], v[52:53] op_sel_hi:[1,0] neg_lo:[0,1] neg_hi:[0,1]
	v_pk_add_f32 v[216:217], v[216:217], v[52:53] op_sel_hi:[1,0] neg_lo:[0,1] neg_hi:[0,1]
	v_pk_add_f32 v[76:77], v[76:77], v[52:53] op_sel_hi:[1,0] neg_lo:[0,1] neg_hi:[0,1]
	v_pk_add_f32 v[218:219], v[218:219], v[52:53] op_sel_hi:[1,0] neg_lo:[0,1] neg_hi:[0,1]
	v_pk_add_f32 v[78:79], v[78:79], v[52:53] op_sel_hi:[1,0] neg_lo:[0,1] neg_hi:[0,1]
	v_pk_add_f32 v[220:221], v[220:221], v[52:53] op_sel_hi:[1,0] neg_lo:[0,1] neg_hi:[0,1]
	v_pk_add_f32 v[80:81], v[80:81], v[52:53] op_sel_hi:[1,0] neg_lo:[0,1] neg_hi:[0,1]
	v_pk_add_f32 v[222:223], v[222:223], v[52:53] op_sel_hi:[1,0] neg_lo:[0,1] neg_hi:[0,1]
	v_pk_mul_f32 v[32:33], v[32:33], v[54:55] op_sel_hi:[1,0]
	v_pk_mul_f32 v[30:31], v[30:31], v[54:55] op_sel_hi:[1,0]
	v_pk_mul_f32 v[28:29], v[28:29], v[54:55] op_sel_hi:[1,0]
	v_pk_mul_f32 v[26:27], v[26:27], v[54:55] op_sel_hi:[1,0]
	v_pk_mul_f32 v[24:25], v[24:25], v[54:55] op_sel_hi:[1,0]
	v_pk_mul_f32 v[22:23], v[22:23], v[54:55] op_sel_hi:[1,0]
	v_pk_mul_f32 v[20:21], v[20:21], v[54:55] op_sel_hi:[1,0]
	v_pk_mul_f32 v[18:19], v[18:19], v[54:55] op_sel_hi:[1,0]
	v_pk_mul_f32 v[16:17], v[16:17], v[54:55] op_sel_hi:[1,0]
	v_pk_mul_f32 v[14:15], v[14:15], v[54:55] op_sel_hi:[1,0]
	v_pk_mul_f32 v[12:13], v[12:13], v[54:55] op_sel_hi:[1,0]
	v_pk_mul_f32 v[10:11], v[10:11], v[54:55] op_sel_hi:[1,0]
	v_pk_mul_f32 v[8:9], v[8:9], v[54:55] op_sel_hi:[1,0]
	v_pk_mul_f32 v[6:7], v[6:7], v[54:55] op_sel_hi:[1,0]
	v_pk_mul_f32 v[4:5], v[4:5], v[54:55] op_sel_hi:[1,0]
	v_pk_mul_f32 v[2:3], v[2:3], v[54:55] op_sel_hi:[1,0]
	v_mul_f32_e32 v82, v82, v54
	v_mov_b32_e32 v51, v50
	v_mov_b32_e32 v52, v50
	v_mov_b32_e32 v53, v50
	v_mov_b32_e32 v54, v50
	v_mov_b32_e32 v55, v50
	v_mov_b32_e32 v56, v50
	v_mov_b32_e32 v57, v50
	v_mov_b32_e32 v58, v50
	v_mov_b32_e32 v59, v50
	v_mov_b32_e32 v60, v50
	v_mov_b32_e32 v61, v50
	v_mov_b32_e32 v62, v50
	v_mov_b32_e32 v63, v50
	v_mov_b32_e32 v64, v50
	v_mov_b32_e32 v65, v50
	v_mov_b32_e32 v34, v50
	v_mov_b32_e32 v35, v50
	v_mov_b32_e32 v36, v50
	v_mov_b32_e32 v37, v50
	v_mov_b32_e32 v38, v50
	v_mov_b32_e32 v39, v50
	v_mov_b32_e32 v40, v50
	v_mov_b32_e32 v41, v50
	v_mov_b32_e32 v42, v50
	v_mov_b32_e32 v43, v50
	v_mov_b32_e32 v44, v50
	v_mov_b32_e32 v45, v50
	v_mov_b32_e32 v46, v50
	v_mov_b32_e32 v47, v50
	v_mov_b32_e32 v48, v50
	v_mov_b32_e32 v49, v50
	s_branch .LBB0_631
